# hand-written GEMM1 epilogue (packed f32 gelu/silu, saddr stores, per-unit scalar setup); stats tiles and last tile keep compiler code
# speedup vs baseline: 1.0200x; 1.0200x over previous
.LBB0_186:
	s_sub_i32 s5, s20, 8
	s_cmp_lt_u32 s5, 8
	s_cbranch_scc1 .Lepz_a_old
	s_mov_b32 s10, 0x11b00000
	s_cmp_lt_u32 s20, 8
	s_cselect_b32 s10, 0xdb00000, s10
	s_cselect_b32 s11, 0, 16
	s_sub_i32 s11, s20, s11
	s_lshl_b32 s11, s11, 16
	s_lshl_b32 s5, s4, 20
	s_add_u32 s10, s10, s11
	s_add_u32 s10, s10, s5
	s_add_u32 s8, s70, s10
	s_addc_u32 s9, s71, 0
	v_and_b32_e32 v184, 15, v222
	v_add_u32_e32 v184, s33, v184
	v_lshlrev_b32_e32 v184, 8, v184
	v_lshrrev_b32_e32 v185, 4, v222
	v_lshlrev_b32_e32 v185, 4, v185
	s_lshl_b32 s5, s34, 1
	v_add3_u32 v184, v184, v185, s5
	v_mov_b32_e32 v176, s82
	v_mov_b32_e32 v177, s82
	v_mov_b32_e32 v182, 1.0
	v_mov_b32_e32 v183, 1.0
	s_cmp_lt_u32 s20, 8
	s_cbranch_scc0 .Lepz_a_silu
	v_mov_b32_e32 v178, 0x3d372713
	v_mov_b32_e32 v179, 0x3d372713
	v_mov_b32_e32 v180, 0xc0135761
	v_mov_b32_e32 v181, 0xc0135761
	v_pk_mul_f32 v[186:187], v[124:125], v[176:177]
	v_pk_mul_f32 v[188:189], v[126:127], v[176:177]
	v_pk_mul_f32 v[190:191], v[120:121], v[176:177]
	v_pk_mul_f32 v[192:193], v[122:123], v[176:177]
	v_pk_mul_f32 v[194:195], v[186:187], v[178:179]
	v_pk_mul_f32 v[196:197], v[188:189], v[178:179]
	v_pk_mul_f32 v[198:199], v[190:191], v[178:179]
	v_pk_mul_f32 v[200:201], v[192:193], v[178:179]
	v_pk_mul_f32 v[194:195], v[186:187], v[194:195]
	v_pk_mul_f32 v[196:197], v[188:189], v[196:197]
	v_pk_mul_f32 v[198:199], v[190:191], v[198:199]
	v_pk_mul_f32 v[200:201], v[192:193], v[200:201]
	v_pk_fma_f32 v[194:195], v[186:187], v[194:195], v[186:187]
	v_pk_fma_f32 v[196:197], v[188:189], v[196:197], v[188:189]
	v_pk_fma_f32 v[198:199], v[190:191], v[198:199], v[190:191]
	v_pk_fma_f32 v[200:201], v[192:193], v[200:201], v[192:193]
	v_pk_mul_f32 v[194:195], v[194:195], v[180:181]
	v_pk_mul_f32 v[196:197], v[196:197], v[180:181]
	v_pk_mul_f32 v[198:199], v[198:199], v[180:181]
	v_pk_mul_f32 v[200:201], v[200:201], v[180:181]
	v_exp_f32_e32 v194, v194
	v_exp_f32_e32 v195, v195
	v_exp_f32_e32 v196, v196
	v_exp_f32_e32 v197, v197
	v_exp_f32_e32 v198, v198
	v_exp_f32_e32 v199, v199
	v_exp_f32_e32 v200, v200
	v_exp_f32_e32 v201, v201
	v_pk_add_f32 v[194:195], v[194:195], v[182:183]
	v_pk_add_f32 v[196:197], v[196:197], v[182:183]
	v_pk_add_f32 v[198:199], v[198:199], v[182:183]
	v_pk_add_f32 v[200:201], v[200:201], v[182:183]
	v_rcp_f32_e32 v194, v194
	v_rcp_f32_e32 v195, v195
	v_rcp_f32_e32 v196, v196
	v_rcp_f32_e32 v197, v197
	v_rcp_f32_e32 v198, v198
	v_rcp_f32_e32 v199, v199
	v_rcp_f32_e32 v200, v200
	v_rcp_f32_e32 v201, v201
	v_pk_mul_f32 v[186:187], v[186:187], v[194:195]
	v_pk_mul_f32 v[188:189], v[188:189], v[196:197]
	v_pk_mul_f32 v[190:191], v[190:191], v[198:199]
	v_pk_mul_f32 v[192:193], v[192:193], v[200:201]
	v_cvt_pk_f16_f32 v202, v186, v187
	v_cvt_pk_f16_f32 v203, v188, v189
	v_cvt_pk_f16_f32 v204, v190, v191
	v_cvt_pk_f16_f32 v205, v192, v193
	global_store_dwordx4 v184, v[202:205], s[8:9]
	v_pk_mul_f32 v[186:187], v[116:117], v[176:177]
	v_pk_mul_f32 v[188:189], v[118:119], v[176:177]
	v_pk_mul_f32 v[190:191], v[112:113], v[176:177]
	v_pk_mul_f32 v[192:193], v[114:115], v[176:177]
	v_pk_mul_f32 v[194:195], v[186:187], v[178:179]
	v_pk_mul_f32 v[196:197], v[188:189], v[178:179]
	v_pk_mul_f32 v[198:199], v[190:191], v[178:179]
	v_pk_mul_f32 v[200:201], v[192:193], v[178:179]
	v_pk_mul_f32 v[194:195], v[186:187], v[194:195]
	v_pk_mul_f32 v[196:197], v[188:189], v[196:197]
	v_pk_mul_f32 v[198:199], v[190:191], v[198:199]
	v_pk_mul_f32 v[200:201], v[192:193], v[200:201]
	v_pk_fma_f32 v[194:195], v[186:187], v[194:195], v[186:187]
	v_pk_fma_f32 v[196:197], v[188:189], v[196:197], v[188:189]
	v_pk_fma_f32 v[198:199], v[190:191], v[198:199], v[190:191]
	v_pk_fma_f32 v[200:201], v[192:193], v[200:201], v[192:193]
	v_pk_mul_f32 v[194:195], v[194:195], v[180:181]
	v_pk_mul_f32 v[196:197], v[196:197], v[180:181]
	v_pk_mul_f32 v[198:199], v[198:199], v[180:181]
	v_pk_mul_f32 v[200:201], v[200:201], v[180:181]
	v_exp_f32_e32 v194, v194
	v_exp_f32_e32 v195, v195
	v_exp_f32_e32 v196, v196
	v_exp_f32_e32 v197, v197
	v_exp_f32_e32 v198, v198
	v_exp_f32_e32 v199, v199
	v_exp_f32_e32 v200, v200
	v_exp_f32_e32 v201, v201
	v_pk_add_f32 v[194:195], v[194:195], v[182:183]
	v_pk_add_f32 v[196:197], v[196:197], v[182:183]
	v_pk_add_f32 v[198:199], v[198:199], v[182:183]
	v_pk_add_f32 v[200:201], v[200:201], v[182:183]
	v_rcp_f32_e32 v194, v194
	v_rcp_f32_e32 v195, v195
	v_rcp_f32_e32 v196, v196
	v_rcp_f32_e32 v197, v197
	v_rcp_f32_e32 v198, v198
	v_rcp_f32_e32 v199, v199
	v_rcp_f32_e32 v200, v200
	v_rcp_f32_e32 v201, v201
	v_pk_mul_f32 v[186:187], v[186:187], v[194:195]
	v_pk_mul_f32 v[188:189], v[188:189], v[196:197]
	v_pk_mul_f32 v[190:191], v[190:191], v[198:199]
	v_pk_mul_f32 v[192:193], v[192:193], v[200:201]
	v_cvt_pk_f16_f32 v206, v186, v187
	v_cvt_pk_f16_f32 v207, v188, v189
	v_cvt_pk_f16_f32 v208, v190, v191
	v_cvt_pk_f16_f32 v209, v192, v193
	v_add_u32_e32 v185, 0x8000, v184
	global_store_dwordx4 v185, v[206:209], s[8:9]
	v_pk_mul_f32 v[186:187], v[108:109], v[176:177]
	v_pk_mul_f32 v[188:189], v[110:111], v[176:177]
	v_pk_mul_f32 v[190:191], v[104:105], v[176:177]
	v_pk_mul_f32 v[192:193], v[106:107], v[176:177]
	v_pk_mul_f32 v[194:195], v[186:187], v[178:179]
	v_pk_mul_f32 v[196:197], v[188:189], v[178:179]
	v_pk_mul_f32 v[198:199], v[190:191], v[178:179]
	v_pk_mul_f32 v[200:201], v[192:193], v[178:179]
	v_pk_mul_f32 v[194:195], v[186:187], v[194:195]
	v_pk_mul_f32 v[196:197], v[188:189], v[196:197]
	v_pk_mul_f32 v[198:199], v[190:191], v[198:199]
	v_pk_mul_f32 v[200:201], v[192:193], v[200:201]
	v_pk_fma_f32 v[194:195], v[186:187], v[194:195], v[186:187]
	v_pk_fma_f32 v[196:197], v[188:189], v[196:197], v[188:189]
	v_pk_fma_f32 v[198:199], v[190:191], v[198:199], v[190:191]
	v_pk_fma_f32 v[200:201], v[192:193], v[200:201], v[192:193]
	v_pk_mul_f32 v[194:195], v[194:195], v[180:181]
	v_pk_mul_f32 v[196:197], v[196:197], v[180:181]
	v_pk_mul_f32 v[198:199], v[198:199], v[180:181]
	v_pk_mul_f32 v[200:201], v[200:201], v[180:181]
	v_exp_f32_e32 v194, v194
	v_exp_f32_e32 v195, v195
	v_exp_f32_e32 v196, v196
	v_exp_f32_e32 v197, v197
	v_exp_f32_e32 v198, v198
	v_exp_f32_e32 v199, v199
	v_exp_f32_e32 v200, v200
	v_exp_f32_e32 v201, v201
	v_pk_add_f32 v[194:195], v[194:195], v[182:183]
	v_pk_add_f32 v[196:197], v[196:197], v[182:183]
	v_pk_add_f32 v[198:199], v[198:199], v[182:183]
	v_pk_add_f32 v[200:201], v[200:201], v[182:183]
	v_rcp_f32_e32 v194, v194
	v_rcp_f32_e32 v195, v195
	v_rcp_f32_e32 v196, v196
	v_rcp_f32_e32 v197, v197
	v_rcp_f32_e32 v198, v198
	v_rcp_f32_e32 v199, v199
	v_rcp_f32_e32 v200, v200
	v_rcp_f32_e32 v201, v201
	v_pk_mul_f32 v[186:187], v[186:187], v[194:195]
	v_pk_mul_f32 v[188:189], v[188:189], v[196:197]
	v_pk_mul_f32 v[190:191], v[190:191], v[198:199]
	v_pk_mul_f32 v[192:193], v[192:193], v[200:201]
	v_cvt_pk_f16_f32 v202, v186, v187
	v_cvt_pk_f16_f32 v203, v188, v189
	v_cvt_pk_f16_f32 v204, v190, v191
	v_cvt_pk_f16_f32 v205, v192, v193
	v_add_u32_e32 v185, 0x1000, v184
	global_store_dwordx4 v185, v[202:205], s[8:9]
	v_pk_mul_f32 v[186:187], v[100:101], v[176:177]
	v_pk_mul_f32 v[188:189], v[102:103], v[176:177]
	v_pk_mul_f32 v[190:191], v[96:97], v[176:177]
	v_pk_mul_f32 v[192:193], v[98:99], v[176:177]
	v_pk_mul_f32 v[194:195], v[186:187], v[178:179]
	v_pk_mul_f32 v[196:197], v[188:189], v[178:179]
	v_pk_mul_f32 v[198:199], v[190:191], v[178:179]
	v_pk_mul_f32 v[200:201], v[192:193], v[178:179]
	v_pk_mul_f32 v[194:195], v[186:187], v[194:195]
	v_pk_mul_f32 v[196:197], v[188:189], v[196:197]
	v_pk_mul_f32 v[198:199], v[190:191], v[198:199]
	v_pk_mul_f32 v[200:201], v[192:193], v[200:201]
	v_pk_fma_f32 v[194:195], v[186:187], v[194:195], v[186:187]
	v_pk_fma_f32 v[196:197], v[188:189], v[196:197], v[188:189]
	v_pk_fma_f32 v[198:199], v[190:191], v[198:199], v[190:191]
	v_pk_fma_f32 v[200:201], v[192:193], v[200:201], v[192:193]
	v_pk_mul_f32 v[194:195], v[194:195], v[180:181]
	v_pk_mul_f32 v[196:197], v[196:197], v[180:181]
	v_pk_mul_f32 v[198:199], v[198:199], v[180:181]
	v_pk_mul_f32 v[200:201], v[200:201], v[180:181]
	v_exp_f32_e32 v194, v194
	v_exp_f32_e32 v195, v195
	v_exp_f32_e32 v196, v196
	v_exp_f32_e32 v197, v197
	v_exp_f32_e32 v198, v198
	v_exp_f32_e32 v199, v199
	v_exp_f32_e32 v200, v200
	v_exp_f32_e32 v201, v201
	v_pk_add_f32 v[194:195], v[194:195], v[182:183]
	v_pk_add_f32 v[196:197], v[196:197], v[182:183]
	v_pk_add_f32 v[198:199], v[198:199], v[182:183]
	v_pk_add_f32 v[200:201], v[200:201], v[182:183]
	v_rcp_f32_e32 v194, v194
	v_rcp_f32_e32 v195, v195
	v_rcp_f32_e32 v196, v196
	v_rcp_f32_e32 v197, v197
	v_rcp_f32_e32 v198, v198
	v_rcp_f32_e32 v199, v199
	v_rcp_f32_e32 v200, v200
	v_rcp_f32_e32 v201, v201
	v_pk_mul_f32 v[186:187], v[186:187], v[194:195]
	v_pk_mul_f32 v[188:189], v[188:189], v[196:197]
	v_pk_mul_f32 v[190:191], v[190:191], v[198:199]
	v_pk_mul_f32 v[192:193], v[192:193], v[200:201]
	v_cvt_pk_f16_f32 v206, v186, v187
	v_cvt_pk_f16_f32 v207, v188, v189
	v_cvt_pk_f16_f32 v208, v190, v191
	v_cvt_pk_f16_f32 v209, v192, v193
	v_add_u32_e32 v185, 0x9000, v184
	global_store_dwordx4 v185, v[206:209], s[8:9]
	v_pk_mul_f32 v[186:187], v[92:93], v[176:177]
	v_pk_mul_f32 v[188:189], v[94:95], v[176:177]
	v_pk_mul_f32 v[190:191], v[88:89], v[176:177]
	v_pk_mul_f32 v[192:193], v[90:91], v[176:177]
	v_pk_mul_f32 v[194:195], v[186:187], v[178:179]
	v_pk_mul_f32 v[196:197], v[188:189], v[178:179]
	v_pk_mul_f32 v[198:199], v[190:191], v[178:179]
	v_pk_mul_f32 v[200:201], v[192:193], v[178:179]
	v_pk_mul_f32 v[194:195], v[186:187], v[194:195]
	v_pk_mul_f32 v[196:197], v[188:189], v[196:197]
	v_pk_mul_f32 v[198:199], v[190:191], v[198:199]
	v_pk_mul_f32 v[200:201], v[192:193], v[200:201]
	v_pk_fma_f32 v[194:195], v[186:187], v[194:195], v[186:187]
	v_pk_fma_f32 v[196:197], v[188:189], v[196:197], v[188:189]
	v_pk_fma_f32 v[198:199], v[190:191], v[198:199], v[190:191]
	v_pk_fma_f32 v[200:201], v[192:193], v[200:201], v[192:193]
	v_pk_mul_f32 v[194:195], v[194:195], v[180:181]
	v_pk_mul_f32 v[196:197], v[196:197], v[180:181]
	v_pk_mul_f32 v[198:199], v[198:199], v[180:181]
	v_pk_mul_f32 v[200:201], v[200:201], v[180:181]
	v_exp_f32_e32 v194, v194
	v_exp_f32_e32 v195, v195
	v_exp_f32_e32 v196, v196
	v_exp_f32_e32 v197, v197
	v_exp_f32_e32 v198, v198
	v_exp_f32_e32 v199, v199
	v_exp_f32_e32 v200, v200
	v_exp_f32_e32 v201, v201
	v_pk_add_f32 v[194:195], v[194:195], v[182:183]
	v_pk_add_f32 v[196:197], v[196:197], v[182:183]
	v_pk_add_f32 v[198:199], v[198:199], v[182:183]
	v_pk_add_f32 v[200:201], v[200:201], v[182:183]
	v_rcp_f32_e32 v194, v194
	v_rcp_f32_e32 v195, v195
	v_rcp_f32_e32 v196, v196
	v_rcp_f32_e32 v197, v197
	v_rcp_f32_e32 v198, v198
	v_rcp_f32_e32 v199, v199
	v_rcp_f32_e32 v200, v200
	v_rcp_f32_e32 v201, v201
	v_pk_mul_f32 v[186:187], v[186:187], v[194:195]
	v_pk_mul_f32 v[188:189], v[188:189], v[196:197]
	v_pk_mul_f32 v[190:191], v[190:191], v[198:199]
	v_pk_mul_f32 v[192:193], v[192:193], v[200:201]
	v_cvt_pk_f16_f32 v202, v186, v187
	v_cvt_pk_f16_f32 v203, v188, v189
	v_cvt_pk_f16_f32 v204, v190, v191
	v_cvt_pk_f16_f32 v205, v192, v193
	v_add_u32_e32 v185, 0x2000, v184
	global_store_dwordx4 v185, v[202:205], s[8:9]
	v_pk_mul_f32 v[186:187], v[84:85], v[176:177]
	v_pk_mul_f32 v[188:189], v[86:87], v[176:177]
	v_pk_mul_f32 v[190:191], v[80:81], v[176:177]
	v_pk_mul_f32 v[192:193], v[82:83], v[176:177]
	v_pk_mul_f32 v[194:195], v[186:187], v[178:179]
	v_pk_mul_f32 v[196:197], v[188:189], v[178:179]
	v_pk_mul_f32 v[198:199], v[190:191], v[178:179]
	v_pk_mul_f32 v[200:201], v[192:193], v[178:179]
	v_pk_mul_f32 v[194:195], v[186:187], v[194:195]
	v_pk_mul_f32 v[196:197], v[188:189], v[196:197]
	v_pk_mul_f32 v[198:199], v[190:191], v[198:199]
	v_pk_mul_f32 v[200:201], v[192:193], v[200:201]
	v_pk_fma_f32 v[194:195], v[186:187], v[194:195], v[186:187]
	v_pk_fma_f32 v[196:197], v[188:189], v[196:197], v[188:189]
	v_pk_fma_f32 v[198:199], v[190:191], v[198:199], v[190:191]
	v_pk_fma_f32 v[200:201], v[192:193], v[200:201], v[192:193]
	v_pk_mul_f32 v[194:195], v[194:195], v[180:181]
	v_pk_mul_f32 v[196:197], v[196:197], v[180:181]
	v_pk_mul_f32 v[198:199], v[198:199], v[180:181]
	v_pk_mul_f32 v[200:201], v[200:201], v[180:181]
	v_exp_f32_e32 v194, v194
	v_exp_f32_e32 v195, v195
	v_exp_f32_e32 v196, v196
	v_exp_f32_e32 v197, v197
	v_exp_f32_e32 v198, v198
	v_exp_f32_e32 v199, v199
	v_exp_f32_e32 v200, v200
	v_exp_f32_e32 v201, v201
	v_pk_add_f32 v[194:195], v[194:195], v[182:183]
	v_pk_add_f32 v[196:197], v[196:197], v[182:183]
	v_pk_add_f32 v[198:199], v[198:199], v[182:183]
	v_pk_add_f32 v[200:201], v[200:201], v[182:183]
	v_rcp_f32_e32 v194, v194
	v_rcp_f32_e32 v195, v195
	v_rcp_f32_e32 v196, v196
	v_rcp_f32_e32 v197, v197
	v_rcp_f32_e32 v198, v198
	v_rcp_f32_e32 v199, v199
	v_rcp_f32_e32 v200, v200
	v_rcp_f32_e32 v201, v201
	v_pk_mul_f32 v[186:187], v[186:187], v[194:195]
	v_pk_mul_f32 v[188:189], v[188:189], v[196:197]
	v_pk_mul_f32 v[190:191], v[190:191], v[198:199]
	v_pk_mul_f32 v[192:193], v[192:193], v[200:201]
	v_cvt_pk_f16_f32 v206, v186, v187
	v_cvt_pk_f16_f32 v207, v188, v189
	v_cvt_pk_f16_f32 v208, v190, v191
	v_cvt_pk_f16_f32 v209, v192, v193
	v_add_u32_e32 v185, 0xa000, v184
	global_store_dwordx4 v185, v[206:209], s[8:9]
	v_pk_mul_f32 v[186:187], v[76:77], v[176:177]
	v_pk_mul_f32 v[188:189], v[78:79], v[176:177]
	v_pk_mul_f32 v[190:191], v[72:73], v[176:177]
	v_pk_mul_f32 v[192:193], v[74:75], v[176:177]
	v_pk_mul_f32 v[194:195], v[186:187], v[178:179]
	v_pk_mul_f32 v[196:197], v[188:189], v[178:179]
	v_pk_mul_f32 v[198:199], v[190:191], v[178:179]
	v_pk_mul_f32 v[200:201], v[192:193], v[178:179]
	v_pk_mul_f32 v[194:195], v[186:187], v[194:195]
	v_pk_mul_f32 v[196:197], v[188:189], v[196:197]
	v_pk_mul_f32 v[198:199], v[190:191], v[198:199]
	v_pk_mul_f32 v[200:201], v[192:193], v[200:201]
	v_pk_fma_f32 v[194:195], v[186:187], v[194:195], v[186:187]
	v_pk_fma_f32 v[196:197], v[188:189], v[196:197], v[188:189]
	v_pk_fma_f32 v[198:199], v[190:191], v[198:199], v[190:191]
	v_pk_fma_f32 v[200:201], v[192:193], v[200:201], v[192:193]
	v_pk_mul_f32 v[194:195], v[194:195], v[180:181]
	v_pk_mul_f32 v[196:197], v[196:197], v[180:181]
	v_pk_mul_f32 v[198:199], v[198:199], v[180:181]
	v_pk_mul_f32 v[200:201], v[200:201], v[180:181]
	v_exp_f32_e32 v194, v194
	v_exp_f32_e32 v195, v195
	v_exp_f32_e32 v196, v196
	v_exp_f32_e32 v197, v197
	v_exp_f32_e32 v198, v198
	v_exp_f32_e32 v199, v199
	v_exp_f32_e32 v200, v200
	v_exp_f32_e32 v201, v201
	v_pk_add_f32 v[194:195], v[194:195], v[182:183]
	v_pk_add_f32 v[196:197], v[196:197], v[182:183]
	v_pk_add_f32 v[198:199], v[198:199], v[182:183]
	v_pk_add_f32 v[200:201], v[200:201], v[182:183]
	v_rcp_f32_e32 v194, v194
	v_rcp_f32_e32 v195, v195
	v_rcp_f32_e32 v196, v196
	v_rcp_f32_e32 v197, v197
	v_rcp_f32_e32 v198, v198
	v_rcp_f32_e32 v199, v199
	v_rcp_f32_e32 v200, v200
	v_rcp_f32_e32 v201, v201
	v_pk_mul_f32 v[186:187], v[186:187], v[194:195]
	v_pk_mul_f32 v[188:189], v[188:189], v[196:197]
	v_pk_mul_f32 v[190:191], v[190:191], v[198:199]
	v_pk_mul_f32 v[192:193], v[192:193], v[200:201]
	v_cvt_pk_f16_f32 v202, v186, v187
	v_cvt_pk_f16_f32 v203, v188, v189
	v_cvt_pk_f16_f32 v204, v190, v191
	v_cvt_pk_f16_f32 v205, v192, v193
	v_add_u32_e32 v185, 0x3000, v184
	global_store_dwordx4 v185, v[202:205], s[8:9]
	v_pk_mul_f32 v[186:187], v[68:69], v[176:177]
	v_pk_mul_f32 v[188:189], v[70:71], v[176:177]
	v_pk_mul_f32 v[190:191], v[64:65], v[176:177]
	v_pk_mul_f32 v[192:193], v[66:67], v[176:177]
	v_pk_mul_f32 v[194:195], v[186:187], v[178:179]
	v_pk_mul_f32 v[196:197], v[188:189], v[178:179]
	v_pk_mul_f32 v[198:199], v[190:191], v[178:179]
	v_pk_mul_f32 v[200:201], v[192:193], v[178:179]
	v_pk_mul_f32 v[194:195], v[186:187], v[194:195]
	v_pk_mul_f32 v[196:197], v[188:189], v[196:197]
	v_pk_mul_f32 v[198:199], v[190:191], v[198:199]
	v_pk_mul_f32 v[200:201], v[192:193], v[200:201]
	v_pk_fma_f32 v[194:195], v[186:187], v[194:195], v[186:187]
	v_pk_fma_f32 v[196:197], v[188:189], v[196:197], v[188:189]
	v_pk_fma_f32 v[198:199], v[190:191], v[198:199], v[190:191]
	v_pk_fma_f32 v[200:201], v[192:193], v[200:201], v[192:193]
	v_pk_mul_f32 v[194:195], v[194:195], v[180:181]
	v_pk_mul_f32 v[196:197], v[196:197], v[180:181]
	v_pk_mul_f32 v[198:199], v[198:199], v[180:181]
	v_pk_mul_f32 v[200:201], v[200:201], v[180:181]
	v_exp_f32_e32 v194, v194
	v_exp_f32_e32 v195, v195
	v_exp_f32_e32 v196, v196
	v_exp_f32_e32 v197, v197
	v_exp_f32_e32 v198, v198
	v_exp_f32_e32 v199, v199
	v_exp_f32_e32 v200, v200
	v_exp_f32_e32 v201, v201
	v_pk_add_f32 v[194:195], v[194:195], v[182:183]
	v_pk_add_f32 v[196:197], v[196:197], v[182:183]
	v_pk_add_f32 v[198:199], v[198:199], v[182:183]
	v_pk_add_f32 v[200:201], v[200:201], v[182:183]
	v_rcp_f32_e32 v194, v194
	v_rcp_f32_e32 v195, v195
	v_rcp_f32_e32 v196, v196
	v_rcp_f32_e32 v197, v197
	v_rcp_f32_e32 v198, v198
	v_rcp_f32_e32 v199, v199
	v_rcp_f32_e32 v200, v200
	v_rcp_f32_e32 v201, v201
	v_pk_mul_f32 v[186:187], v[186:187], v[194:195]
	v_pk_mul_f32 v[188:189], v[188:189], v[196:197]
	v_pk_mul_f32 v[190:191], v[190:191], v[198:199]
	v_pk_mul_f32 v[192:193], v[192:193], v[200:201]
	v_cvt_pk_f16_f32 v206, v186, v187
	v_cvt_pk_f16_f32 v207, v188, v189
	v_cvt_pk_f16_f32 v208, v190, v191
	v_cvt_pk_f16_f32 v209, v192, v193
	v_add_u32_e32 v185, 0xb000, v184
	global_store_dwordx4 v185, v[206:209], s[8:9]
	v_pk_mul_f32 v[186:187], v[60:61], v[176:177]
	v_pk_mul_f32 v[188:189], v[62:63], v[176:177]
	v_pk_mul_f32 v[190:191], v[56:57], v[176:177]
	v_pk_mul_f32 v[192:193], v[58:59], v[176:177]
	v_pk_mul_f32 v[194:195], v[186:187], v[178:179]
	v_pk_mul_f32 v[196:197], v[188:189], v[178:179]
	v_pk_mul_f32 v[198:199], v[190:191], v[178:179]
	v_pk_mul_f32 v[200:201], v[192:193], v[178:179]
	v_pk_mul_f32 v[194:195], v[186:187], v[194:195]
	v_pk_mul_f32 v[196:197], v[188:189], v[196:197]
	v_pk_mul_f32 v[198:199], v[190:191], v[198:199]
	v_pk_mul_f32 v[200:201], v[192:193], v[200:201]
	v_pk_fma_f32 v[194:195], v[186:187], v[194:195], v[186:187]
	v_pk_fma_f32 v[196:197], v[188:189], v[196:197], v[188:189]
	v_pk_fma_f32 v[198:199], v[190:191], v[198:199], v[190:191]
	v_pk_fma_f32 v[200:201], v[192:193], v[200:201], v[192:193]
	v_pk_mul_f32 v[194:195], v[194:195], v[180:181]
	v_pk_mul_f32 v[196:197], v[196:197], v[180:181]
	v_pk_mul_f32 v[198:199], v[198:199], v[180:181]
	v_pk_mul_f32 v[200:201], v[200:201], v[180:181]
	v_exp_f32_e32 v194, v194
	v_exp_f32_e32 v195, v195
	v_exp_f32_e32 v196, v196
	v_exp_f32_e32 v197, v197
	v_exp_f32_e32 v198, v198
	v_exp_f32_e32 v199, v199
	v_exp_f32_e32 v200, v200
	v_exp_f32_e32 v201, v201
	v_pk_add_f32 v[194:195], v[194:195], v[182:183]
	v_pk_add_f32 v[196:197], v[196:197], v[182:183]
	v_pk_add_f32 v[198:199], v[198:199], v[182:183]
	v_pk_add_f32 v[200:201], v[200:201], v[182:183]
	v_rcp_f32_e32 v194, v194
	v_rcp_f32_e32 v195, v195
	v_rcp_f32_e32 v196, v196
	v_rcp_f32_e32 v197, v197
	v_rcp_f32_e32 v198, v198
	v_rcp_f32_e32 v199, v199
	v_rcp_f32_e32 v200, v200
	v_rcp_f32_e32 v201, v201
	v_pk_mul_f32 v[186:187], v[186:187], v[194:195]
	v_pk_mul_f32 v[188:189], v[188:189], v[196:197]
	v_pk_mul_f32 v[190:191], v[190:191], v[198:199]
	v_pk_mul_f32 v[192:193], v[192:193], v[200:201]
	v_cvt_pk_f16_f32 v202, v186, v187
	v_cvt_pk_f16_f32 v203, v188, v189
	v_cvt_pk_f16_f32 v204, v190, v191
	v_cvt_pk_f16_f32 v205, v192, v193
	v_add_u32_e32 v185, 0x80000, v184
	global_store_dwordx4 v185, v[202:205], s[8:9]
	v_pk_mul_f32 v[186:187], v[52:53], v[176:177]
	v_pk_mul_f32 v[188:189], v[54:55], v[176:177]
	v_pk_mul_f32 v[190:191], v[48:49], v[176:177]
	v_pk_mul_f32 v[192:193], v[50:51], v[176:177]
	v_pk_mul_f32 v[194:195], v[186:187], v[178:179]
	v_pk_mul_f32 v[196:197], v[188:189], v[178:179]
	v_pk_mul_f32 v[198:199], v[190:191], v[178:179]
	v_pk_mul_f32 v[200:201], v[192:193], v[178:179]
	v_pk_mul_f32 v[194:195], v[186:187], v[194:195]
	v_pk_mul_f32 v[196:197], v[188:189], v[196:197]
	v_pk_mul_f32 v[198:199], v[190:191], v[198:199]
	v_pk_mul_f32 v[200:201], v[192:193], v[200:201]
	v_pk_fma_f32 v[194:195], v[186:187], v[194:195], v[186:187]
	v_pk_fma_f32 v[196:197], v[188:189], v[196:197], v[188:189]
	v_pk_fma_f32 v[198:199], v[190:191], v[198:199], v[190:191]
	v_pk_fma_f32 v[200:201], v[192:193], v[200:201], v[192:193]
	v_pk_mul_f32 v[194:195], v[194:195], v[180:181]
	v_pk_mul_f32 v[196:197], v[196:197], v[180:181]
	v_pk_mul_f32 v[198:199], v[198:199], v[180:181]
	v_pk_mul_f32 v[200:201], v[200:201], v[180:181]
	v_exp_f32_e32 v194, v194
	v_exp_f32_e32 v195, v195
	v_exp_f32_e32 v196, v196
	v_exp_f32_e32 v197, v197
	v_exp_f32_e32 v198, v198
	v_exp_f32_e32 v199, v199
	v_exp_f32_e32 v200, v200
	v_exp_f32_e32 v201, v201
	v_pk_add_f32 v[194:195], v[194:195], v[182:183]
	v_pk_add_f32 v[196:197], v[196:197], v[182:183]
	v_pk_add_f32 v[198:199], v[198:199], v[182:183]
	v_pk_add_f32 v[200:201], v[200:201], v[182:183]
	v_rcp_f32_e32 v194, v194
	v_rcp_f32_e32 v195, v195
	v_rcp_f32_e32 v196, v196
	v_rcp_f32_e32 v197, v197
	v_rcp_f32_e32 v198, v198
	v_rcp_f32_e32 v199, v199
	v_rcp_f32_e32 v200, v200
	v_rcp_f32_e32 v201, v201
	v_pk_mul_f32 v[186:187], v[186:187], v[194:195]
	v_pk_mul_f32 v[188:189], v[188:189], v[196:197]
	v_pk_mul_f32 v[190:191], v[190:191], v[198:199]
	v_pk_mul_f32 v[192:193], v[192:193], v[200:201]
	v_cvt_pk_f16_f32 v206, v186, v187
	v_cvt_pk_f16_f32 v207, v188, v189
	v_cvt_pk_f16_f32 v208, v190, v191
	v_cvt_pk_f16_f32 v209, v192, v193
	v_add_u32_e32 v185, 0x88000, v184
	global_store_dwordx4 v185, v[206:209], s[8:9]
	v_pk_mul_f32 v[186:187], v[44:45], v[176:177]
	v_pk_mul_f32 v[188:189], v[46:47], v[176:177]
	v_pk_mul_f32 v[190:191], v[40:41], v[176:177]
	v_pk_mul_f32 v[192:193], v[42:43], v[176:177]
	v_pk_mul_f32 v[194:195], v[186:187], v[178:179]
	v_pk_mul_f32 v[196:197], v[188:189], v[178:179]
	v_pk_mul_f32 v[198:199], v[190:191], v[178:179]
	v_pk_mul_f32 v[200:201], v[192:193], v[178:179]
	v_pk_mul_f32 v[194:195], v[186:187], v[194:195]
	v_pk_mul_f32 v[196:197], v[188:189], v[196:197]
	v_pk_mul_f32 v[198:199], v[190:191], v[198:199]
	v_pk_mul_f32 v[200:201], v[192:193], v[200:201]
	v_pk_fma_f32 v[194:195], v[186:187], v[194:195], v[186:187]
	v_pk_fma_f32 v[196:197], v[188:189], v[196:197], v[188:189]
	v_pk_fma_f32 v[198:199], v[190:191], v[198:199], v[190:191]
	v_pk_fma_f32 v[200:201], v[192:193], v[200:201], v[192:193]
	v_pk_mul_f32 v[194:195], v[194:195], v[180:181]
	v_pk_mul_f32 v[196:197], v[196:197], v[180:181]
	v_pk_mul_f32 v[198:199], v[198:199], v[180:181]
	v_pk_mul_f32 v[200:201], v[200:201], v[180:181]
	v_exp_f32_e32 v194, v194
	v_exp_f32_e32 v195, v195
	v_exp_f32_e32 v196, v196
	v_exp_f32_e32 v197, v197
	v_exp_f32_e32 v198, v198
	v_exp_f32_e32 v199, v199
	v_exp_f32_e32 v200, v200
	v_exp_f32_e32 v201, v201
	v_pk_add_f32 v[194:195], v[194:195], v[182:183]
	v_pk_add_f32 v[196:197], v[196:197], v[182:183]
	v_pk_add_f32 v[198:199], v[198:199], v[182:183]
	v_pk_add_f32 v[200:201], v[200:201], v[182:183]
	v_rcp_f32_e32 v194, v194
	v_rcp_f32_e32 v195, v195
	v_rcp_f32_e32 v196, v196
	v_rcp_f32_e32 v197, v197
	v_rcp_f32_e32 v198, v198
	v_rcp_f32_e32 v199, v199
	v_rcp_f32_e32 v200, v200
	v_rcp_f32_e32 v201, v201
	v_pk_mul_f32 v[186:187], v[186:187], v[194:195]
	v_pk_mul_f32 v[188:189], v[188:189], v[196:197]
	v_pk_mul_f32 v[190:191], v[190:191], v[198:199]
	v_pk_mul_f32 v[192:193], v[192:193], v[200:201]
	v_cvt_pk_f16_f32 v202, v186, v187
	v_cvt_pk_f16_f32 v203, v188, v189
	v_cvt_pk_f16_f32 v204, v190, v191
	v_cvt_pk_f16_f32 v205, v192, v193
	v_add_u32_e32 v185, 0x81000, v184
	global_store_dwordx4 v185, v[202:205], s[8:9]
	v_pk_mul_f32 v[186:187], v[36:37], v[176:177]
	v_pk_mul_f32 v[188:189], v[38:39], v[176:177]
	v_pk_mul_f32 v[190:191], v[32:33], v[176:177]
	v_pk_mul_f32 v[192:193], v[34:35], v[176:177]
	v_pk_mul_f32 v[194:195], v[186:187], v[178:179]
	v_pk_mul_f32 v[196:197], v[188:189], v[178:179]
	v_pk_mul_f32 v[198:199], v[190:191], v[178:179]
	v_pk_mul_f32 v[200:201], v[192:193], v[178:179]
	v_pk_mul_f32 v[194:195], v[186:187], v[194:195]
	v_pk_mul_f32 v[196:197], v[188:189], v[196:197]
	v_pk_mul_f32 v[198:199], v[190:191], v[198:199]
	v_pk_mul_f32 v[200:201], v[192:193], v[200:201]
	v_pk_fma_f32 v[194:195], v[186:187], v[194:195], v[186:187]
	v_pk_fma_f32 v[196:197], v[188:189], v[196:197], v[188:189]
	v_pk_fma_f32 v[198:199], v[190:191], v[198:199], v[190:191]
	v_pk_fma_f32 v[200:201], v[192:193], v[200:201], v[192:193]
	v_pk_mul_f32 v[194:195], v[194:195], v[180:181]
	v_pk_mul_f32 v[196:197], v[196:197], v[180:181]
	v_pk_mul_f32 v[198:199], v[198:199], v[180:181]
	v_pk_mul_f32 v[200:201], v[200:201], v[180:181]
	v_exp_f32_e32 v194, v194
	v_exp_f32_e32 v195, v195
	v_exp_f32_e32 v196, v196
	v_exp_f32_e32 v197, v197
	v_exp_f32_e32 v198, v198
	v_exp_f32_e32 v199, v199
	v_exp_f32_e32 v200, v200
	v_exp_f32_e32 v201, v201
	v_pk_add_f32 v[194:195], v[194:195], v[182:183]
	v_pk_add_f32 v[196:197], v[196:197], v[182:183]
	v_pk_add_f32 v[198:199], v[198:199], v[182:183]
	v_pk_add_f32 v[200:201], v[200:201], v[182:183]
	v_rcp_f32_e32 v194, v194
	v_rcp_f32_e32 v195, v195
	v_rcp_f32_e32 v196, v196
	v_rcp_f32_e32 v197, v197
	v_rcp_f32_e32 v198, v198
	v_rcp_f32_e32 v199, v199
	v_rcp_f32_e32 v200, v200
	v_rcp_f32_e32 v201, v201
	v_pk_mul_f32 v[186:187], v[186:187], v[194:195]
	v_pk_mul_f32 v[188:189], v[188:189], v[196:197]
	v_pk_mul_f32 v[190:191], v[190:191], v[198:199]
	v_pk_mul_f32 v[192:193], v[192:193], v[200:201]
	v_cvt_pk_f16_f32 v206, v186, v187
	v_cvt_pk_f16_f32 v207, v188, v189
	v_cvt_pk_f16_f32 v208, v190, v191
	v_cvt_pk_f16_f32 v209, v192, v193
	v_add_u32_e32 v185, 0x89000, v184
	global_store_dwordx4 v185, v[206:209], s[8:9]
	v_pk_mul_f32 v[186:187], v[28:29], v[176:177]
	v_pk_mul_f32 v[188:189], v[30:31], v[176:177]
	v_pk_mul_f32 v[190:191], v[24:25], v[176:177]
	v_pk_mul_f32 v[192:193], v[26:27], v[176:177]
	v_pk_mul_f32 v[194:195], v[186:187], v[178:179]
	v_pk_mul_f32 v[196:197], v[188:189], v[178:179]
	v_pk_mul_f32 v[198:199], v[190:191], v[178:179]
	v_pk_mul_f32 v[200:201], v[192:193], v[178:179]
	v_pk_mul_f32 v[194:195], v[186:187], v[194:195]
	v_pk_mul_f32 v[196:197], v[188:189], v[196:197]
	v_pk_mul_f32 v[198:199], v[190:191], v[198:199]
	v_pk_mul_f32 v[200:201], v[192:193], v[200:201]
	v_pk_fma_f32 v[194:195], v[186:187], v[194:195], v[186:187]
	v_pk_fma_f32 v[196:197], v[188:189], v[196:197], v[188:189]
	v_pk_fma_f32 v[198:199], v[190:191], v[198:199], v[190:191]
	v_pk_fma_f32 v[200:201], v[192:193], v[200:201], v[192:193]
	v_pk_mul_f32 v[194:195], v[194:195], v[180:181]
	v_pk_mul_f32 v[196:197], v[196:197], v[180:181]
	v_pk_mul_f32 v[198:199], v[198:199], v[180:181]
	v_pk_mul_f32 v[200:201], v[200:201], v[180:181]
	v_exp_f32_e32 v194, v194
	v_exp_f32_e32 v195, v195
	v_exp_f32_e32 v196, v196
	v_exp_f32_e32 v197, v197
	v_exp_f32_e32 v198, v198
	v_exp_f32_e32 v199, v199
	v_exp_f32_e32 v200, v200
	v_exp_f32_e32 v201, v201
	v_pk_add_f32 v[194:195], v[194:195], v[182:183]
	v_pk_add_f32 v[196:197], v[196:197], v[182:183]
	v_pk_add_f32 v[198:199], v[198:199], v[182:183]
	v_pk_add_f32 v[200:201], v[200:201], v[182:183]
	v_rcp_f32_e32 v194, v194
	v_rcp_f32_e32 v195, v195
	v_rcp_f32_e32 v196, v196
	v_rcp_f32_e32 v197, v197
	v_rcp_f32_e32 v198, v198
	v_rcp_f32_e32 v199, v199
	v_rcp_f32_e32 v200, v200
	v_rcp_f32_e32 v201, v201
	v_pk_mul_f32 v[186:187], v[186:187], v[194:195]
	v_pk_mul_f32 v[188:189], v[188:189], v[196:197]
	v_pk_mul_f32 v[190:191], v[190:191], v[198:199]
	v_pk_mul_f32 v[192:193], v[192:193], v[200:201]
	v_cvt_pk_f16_f32 v202, v186, v187
	v_cvt_pk_f16_f32 v203, v188, v189
	v_cvt_pk_f16_f32 v204, v190, v191
	v_cvt_pk_f16_f32 v205, v192, v193
	v_add_u32_e32 v185, 0x82000, v184
	global_store_dwordx4 v185, v[202:205], s[8:9]
	v_pk_mul_f32 v[186:187], v[20:21], v[176:177]
	v_pk_mul_f32 v[188:189], v[22:23], v[176:177]
	v_pk_mul_f32 v[190:191], v[16:17], v[176:177]
	v_pk_mul_f32 v[192:193], v[18:19], v[176:177]
	v_pk_mul_f32 v[194:195], v[186:187], v[178:179]
	v_pk_mul_f32 v[196:197], v[188:189], v[178:179]
	v_pk_mul_f32 v[198:199], v[190:191], v[178:179]
	v_pk_mul_f32 v[200:201], v[192:193], v[178:179]
	v_pk_mul_f32 v[194:195], v[186:187], v[194:195]
	v_pk_mul_f32 v[196:197], v[188:189], v[196:197]
	v_pk_mul_f32 v[198:199], v[190:191], v[198:199]
	v_pk_mul_f32 v[200:201], v[192:193], v[200:201]
	v_pk_fma_f32 v[194:195], v[186:187], v[194:195], v[186:187]
	v_pk_fma_f32 v[196:197], v[188:189], v[196:197], v[188:189]
	v_pk_fma_f32 v[198:199], v[190:191], v[198:199], v[190:191]
	v_pk_fma_f32 v[200:201], v[192:193], v[200:201], v[192:193]
	v_pk_mul_f32 v[194:195], v[194:195], v[180:181]
	v_pk_mul_f32 v[196:197], v[196:197], v[180:181]
	v_pk_mul_f32 v[198:199], v[198:199], v[180:181]
	v_pk_mul_f32 v[200:201], v[200:201], v[180:181]
	v_exp_f32_e32 v194, v194
	v_exp_f32_e32 v195, v195
	v_exp_f32_e32 v196, v196
	v_exp_f32_e32 v197, v197
	v_exp_f32_e32 v198, v198
	v_exp_f32_e32 v199, v199
	v_exp_f32_e32 v200, v200
	v_exp_f32_e32 v201, v201
	v_pk_add_f32 v[194:195], v[194:195], v[182:183]
	v_pk_add_f32 v[196:197], v[196:197], v[182:183]
	v_pk_add_f32 v[198:199], v[198:199], v[182:183]
	v_pk_add_f32 v[200:201], v[200:201], v[182:183]
	v_rcp_f32_e32 v194, v194
	v_rcp_f32_e32 v195, v195
	v_rcp_f32_e32 v196, v196
	v_rcp_f32_e32 v197, v197
	v_rcp_f32_e32 v198, v198
	v_rcp_f32_e32 v199, v199
	v_rcp_f32_e32 v200, v200
	v_rcp_f32_e32 v201, v201
	v_pk_mul_f32 v[186:187], v[186:187], v[194:195]
	v_pk_mul_f32 v[188:189], v[188:189], v[196:197]
	v_pk_mul_f32 v[190:191], v[190:191], v[198:199]
	v_pk_mul_f32 v[192:193], v[192:193], v[200:201]
	v_cvt_pk_f16_f32 v206, v186, v187
	v_cvt_pk_f16_f32 v207, v188, v189
	v_cvt_pk_f16_f32 v208, v190, v191
	v_cvt_pk_f16_f32 v209, v192, v193
	v_add_u32_e32 v185, 0x8a000, v184
	global_store_dwordx4 v185, v[206:209], s[8:9]
	v_pk_mul_f32 v[186:187], v[12:13], v[176:177]
	v_pk_mul_f32 v[188:189], v[14:15], v[176:177]
	v_pk_mul_f32 v[190:191], v[8:9], v[176:177]
	v_pk_mul_f32 v[192:193], v[10:11], v[176:177]
	v_pk_mul_f32 v[194:195], v[186:187], v[178:179]
	v_pk_mul_f32 v[196:197], v[188:189], v[178:179]
	v_pk_mul_f32 v[198:199], v[190:191], v[178:179]
	v_pk_mul_f32 v[200:201], v[192:193], v[178:179]
	v_pk_mul_f32 v[194:195], v[186:187], v[194:195]
	v_pk_mul_f32 v[196:197], v[188:189], v[196:197]
	v_pk_mul_f32 v[198:199], v[190:191], v[198:199]
	v_pk_mul_f32 v[200:201], v[192:193], v[200:201]
	v_pk_fma_f32 v[194:195], v[186:187], v[194:195], v[186:187]
	v_pk_fma_f32 v[196:197], v[188:189], v[196:197], v[188:189]
	v_pk_fma_f32 v[198:199], v[190:191], v[198:199], v[190:191]
	v_pk_fma_f32 v[200:201], v[192:193], v[200:201], v[192:193]
	v_pk_mul_f32 v[194:195], v[194:195], v[180:181]
	v_pk_mul_f32 v[196:197], v[196:197], v[180:181]
	v_pk_mul_f32 v[198:199], v[198:199], v[180:181]
	v_pk_mul_f32 v[200:201], v[200:201], v[180:181]
	v_exp_f32_e32 v194, v194
	v_exp_f32_e32 v195, v195
	v_exp_f32_e32 v196, v196
	v_exp_f32_e32 v197, v197
	v_exp_f32_e32 v198, v198
	v_exp_f32_e32 v199, v199
	v_exp_f32_e32 v200, v200
	v_exp_f32_e32 v201, v201
	v_pk_add_f32 v[194:195], v[194:195], v[182:183]
	v_pk_add_f32 v[196:197], v[196:197], v[182:183]
	v_pk_add_f32 v[198:199], v[198:199], v[182:183]
	v_pk_add_f32 v[200:201], v[200:201], v[182:183]
	v_rcp_f32_e32 v194, v194
	v_rcp_f32_e32 v195, v195
	v_rcp_f32_e32 v196, v196
	v_rcp_f32_e32 v197, v197
	v_rcp_f32_e32 v198, v198
	v_rcp_f32_e32 v199, v199
	v_rcp_f32_e32 v200, v200
	v_rcp_f32_e32 v201, v201
	v_pk_mul_f32 v[186:187], v[186:187], v[194:195]
	v_pk_mul_f32 v[188:189], v[188:189], v[196:197]
	v_pk_mul_f32 v[190:191], v[190:191], v[198:199]
	v_pk_mul_f32 v[192:193], v[192:193], v[200:201]
	v_cvt_pk_f16_f32 v202, v186, v187
	v_cvt_pk_f16_f32 v203, v188, v189
	v_cvt_pk_f16_f32 v204, v190, v191
	v_cvt_pk_f16_f32 v205, v192, v193
	v_add_u32_e32 v185, 0x83000, v184
	global_store_dwordx4 v185, v[202:205], s[8:9]
	v_pk_mul_f32 v[186:187], v[4:5], v[176:177]
	v_pk_mul_f32 v[188:189], v[6:7], v[176:177]
	v_pk_mul_f32 v[190:191], v[0:1], v[176:177]
	v_pk_mul_f32 v[192:193], v[2:3], v[176:177]
	v_pk_mul_f32 v[194:195], v[186:187], v[178:179]
	v_pk_mul_f32 v[196:197], v[188:189], v[178:179]
	v_pk_mul_f32 v[198:199], v[190:191], v[178:179]
	v_pk_mul_f32 v[200:201], v[192:193], v[178:179]
	v_pk_mul_f32 v[194:195], v[186:187], v[194:195]
	v_pk_mul_f32 v[196:197], v[188:189], v[196:197]
	v_pk_mul_f32 v[198:199], v[190:191], v[198:199]
	v_pk_mul_f32 v[200:201], v[192:193], v[200:201]
	v_pk_fma_f32 v[194:195], v[186:187], v[194:195], v[186:187]
	v_pk_fma_f32 v[196:197], v[188:189], v[196:197], v[188:189]
	v_pk_fma_f32 v[198:199], v[190:191], v[198:199], v[190:191]
	v_pk_fma_f32 v[200:201], v[192:193], v[200:201], v[192:193]
	v_pk_mul_f32 v[194:195], v[194:195], v[180:181]
	v_pk_mul_f32 v[196:197], v[196:197], v[180:181]
	v_pk_mul_f32 v[198:199], v[198:199], v[180:181]
	v_pk_mul_f32 v[200:201], v[200:201], v[180:181]
	v_exp_f32_e32 v194, v194
	v_exp_f32_e32 v195, v195
	v_exp_f32_e32 v196, v196
	v_exp_f32_e32 v197, v197
	v_exp_f32_e32 v198, v198
	v_exp_f32_e32 v199, v199
	v_exp_f32_e32 v200, v200
	v_exp_f32_e32 v201, v201
	v_pk_add_f32 v[194:195], v[194:195], v[182:183]
	v_pk_add_f32 v[196:197], v[196:197], v[182:183]
	v_pk_add_f32 v[198:199], v[198:199], v[182:183]
	v_pk_add_f32 v[200:201], v[200:201], v[182:183]
	v_rcp_f32_e32 v194, v194
	v_rcp_f32_e32 v195, v195
	v_rcp_f32_e32 v196, v196
	v_rcp_f32_e32 v197, v197
	v_rcp_f32_e32 v198, v198
	v_rcp_f32_e32 v199, v199
	v_rcp_f32_e32 v200, v200
	v_rcp_f32_e32 v201, v201
	v_pk_mul_f32 v[186:187], v[186:187], v[194:195]
	v_pk_mul_f32 v[188:189], v[188:189], v[196:197]
	v_pk_mul_f32 v[190:191], v[190:191], v[198:199]
	v_pk_mul_f32 v[192:193], v[192:193], v[200:201]
	v_cvt_pk_f16_f32 v206, v186, v187
	v_cvt_pk_f16_f32 v207, v188, v189
	v_cvt_pk_f16_f32 v208, v190, v191
	v_cvt_pk_f16_f32 v209, v192, v193
	v_add_u32_e32 v185, 0x8b000, v184
	global_store_dwordx4 v185, v[206:209], s[8:9]
	s_branch .LBB0_568
.Lepz_a_silu:
	v_mov_b32_e32 v178, 0xbfb8aa3b
	v_mov_b32_e32 v179, 0xbfb8aa3b
	v_pk_mul_f32 v[186:187], v[124:125], v[176:177]
	v_pk_mul_f32 v[188:189], v[126:127], v[176:177]
	v_pk_mul_f32 v[190:191], v[120:121], v[176:177]
	v_pk_mul_f32 v[192:193], v[122:123], v[176:177]
	v_pk_mul_f32 v[194:195], v[186:187], v[178:179]
	v_pk_mul_f32 v[196:197], v[188:189], v[178:179]
	v_pk_mul_f32 v[198:199], v[190:191], v[178:179]
	v_pk_mul_f32 v[200:201], v[192:193], v[178:179]
	v_exp_f32_e32 v194, v194
	v_exp_f32_e32 v195, v195
	v_exp_f32_e32 v196, v196
	v_exp_f32_e32 v197, v197
	v_exp_f32_e32 v198, v198
	v_exp_f32_e32 v199, v199
	v_exp_f32_e32 v200, v200
	v_exp_f32_e32 v201, v201
	v_pk_add_f32 v[194:195], v[194:195], v[182:183]
	v_pk_add_f32 v[196:197], v[196:197], v[182:183]
	v_pk_add_f32 v[198:199], v[198:199], v[182:183]
	v_pk_add_f32 v[200:201], v[200:201], v[182:183]
	v_rcp_f32_e32 v194, v194
	v_rcp_f32_e32 v195, v195
	v_rcp_f32_e32 v196, v196
	v_rcp_f32_e32 v197, v197
	v_rcp_f32_e32 v198, v198
	v_rcp_f32_e32 v199, v199
	v_rcp_f32_e32 v200, v200
	v_rcp_f32_e32 v201, v201
	v_pk_mul_f32 v[186:187], v[186:187], v[194:195]
	v_pk_mul_f32 v[188:189], v[188:189], v[196:197]
	v_pk_mul_f32 v[190:191], v[190:191], v[198:199]
	v_pk_mul_f32 v[192:193], v[192:193], v[200:201]
	v_cvt_pk_f16_f32 v202, v186, v187
	v_cvt_pk_f16_f32 v203, v188, v189
	v_cvt_pk_f16_f32 v204, v190, v191
	v_cvt_pk_f16_f32 v205, v192, v193
	global_store_dwordx4 v184, v[202:205], s[8:9]
	v_pk_mul_f32 v[186:187], v[116:117], v[176:177]
	v_pk_mul_f32 v[188:189], v[118:119], v[176:177]
	v_pk_mul_f32 v[190:191], v[112:113], v[176:177]
	v_pk_mul_f32 v[192:193], v[114:115], v[176:177]
	v_pk_mul_f32 v[194:195], v[186:187], v[178:179]
	v_pk_mul_f32 v[196:197], v[188:189], v[178:179]
	v_pk_mul_f32 v[198:199], v[190:191], v[178:179]
	v_pk_mul_f32 v[200:201], v[192:193], v[178:179]
	v_exp_f32_e32 v194, v194
	v_exp_f32_e32 v195, v195
	v_exp_f32_e32 v196, v196
	v_exp_f32_e32 v197, v197
	v_exp_f32_e32 v198, v198
	v_exp_f32_e32 v199, v199
	v_exp_f32_e32 v200, v200
	v_exp_f32_e32 v201, v201
	v_pk_add_f32 v[194:195], v[194:195], v[182:183]
	v_pk_add_f32 v[196:197], v[196:197], v[182:183]
	v_pk_add_f32 v[198:199], v[198:199], v[182:183]
	v_pk_add_f32 v[200:201], v[200:201], v[182:183]
	v_rcp_f32_e32 v194, v194
	v_rcp_f32_e32 v195, v195
	v_rcp_f32_e32 v196, v196
	v_rcp_f32_e32 v197, v197
	v_rcp_f32_e32 v198, v198
	v_rcp_f32_e32 v199, v199
	v_rcp_f32_e32 v200, v200
	v_rcp_f32_e32 v201, v201
	v_pk_mul_f32 v[186:187], v[186:187], v[194:195]
	v_pk_mul_f32 v[188:189], v[188:189], v[196:197]
	v_pk_mul_f32 v[190:191], v[190:191], v[198:199]
	v_pk_mul_f32 v[192:193], v[192:193], v[200:201]
	v_cvt_pk_f16_f32 v206, v186, v187
	v_cvt_pk_f16_f32 v207, v188, v189
	v_cvt_pk_f16_f32 v208, v190, v191
	v_cvt_pk_f16_f32 v209, v192, v193
	v_add_u32_e32 v185, 0x8000, v184
	global_store_dwordx4 v185, v[206:209], s[8:9]
	v_pk_mul_f32 v[186:187], v[108:109], v[176:177]
	v_pk_mul_f32 v[188:189], v[110:111], v[176:177]
	v_pk_mul_f32 v[190:191], v[104:105], v[176:177]
	v_pk_mul_f32 v[192:193], v[106:107], v[176:177]
	v_pk_mul_f32 v[194:195], v[186:187], v[178:179]
	v_pk_mul_f32 v[196:197], v[188:189], v[178:179]
	v_pk_mul_f32 v[198:199], v[190:191], v[178:179]
	v_pk_mul_f32 v[200:201], v[192:193], v[178:179]
	v_exp_f32_e32 v194, v194
	v_exp_f32_e32 v195, v195
	v_exp_f32_e32 v196, v196
	v_exp_f32_e32 v197, v197
	v_exp_f32_e32 v198, v198
	v_exp_f32_e32 v199, v199
	v_exp_f32_e32 v200, v200
	v_exp_f32_e32 v201, v201
	v_pk_add_f32 v[194:195], v[194:195], v[182:183]
	v_pk_add_f32 v[196:197], v[196:197], v[182:183]
	v_pk_add_f32 v[198:199], v[198:199], v[182:183]
	v_pk_add_f32 v[200:201], v[200:201], v[182:183]
	v_rcp_f32_e32 v194, v194
	v_rcp_f32_e32 v195, v195
	v_rcp_f32_e32 v196, v196
	v_rcp_f32_e32 v197, v197
	v_rcp_f32_e32 v198, v198
	v_rcp_f32_e32 v199, v199
	v_rcp_f32_e32 v200, v200
	v_rcp_f32_e32 v201, v201
	v_pk_mul_f32 v[186:187], v[186:187], v[194:195]
	v_pk_mul_f32 v[188:189], v[188:189], v[196:197]
	v_pk_mul_f32 v[190:191], v[190:191], v[198:199]
	v_pk_mul_f32 v[192:193], v[192:193], v[200:201]
	v_cvt_pk_f16_f32 v202, v186, v187
	v_cvt_pk_f16_f32 v203, v188, v189
	v_cvt_pk_f16_f32 v204, v190, v191
	v_cvt_pk_f16_f32 v205, v192, v193
	v_add_u32_e32 v185, 0x1000, v184
	global_store_dwordx4 v185, v[202:205], s[8:9]
	v_pk_mul_f32 v[186:187], v[100:101], v[176:177]
	v_pk_mul_f32 v[188:189], v[102:103], v[176:177]
	v_pk_mul_f32 v[190:191], v[96:97], v[176:177]
	v_pk_mul_f32 v[192:193], v[98:99], v[176:177]
	v_pk_mul_f32 v[194:195], v[186:187], v[178:179]
	v_pk_mul_f32 v[196:197], v[188:189], v[178:179]
	v_pk_mul_f32 v[198:199], v[190:191], v[178:179]
	v_pk_mul_f32 v[200:201], v[192:193], v[178:179]
	v_exp_f32_e32 v194, v194
	v_exp_f32_e32 v195, v195
	v_exp_f32_e32 v196, v196
	v_exp_f32_e32 v197, v197
	v_exp_f32_e32 v198, v198
	v_exp_f32_e32 v199, v199
	v_exp_f32_e32 v200, v200
	v_exp_f32_e32 v201, v201
	v_pk_add_f32 v[194:195], v[194:195], v[182:183]
	v_pk_add_f32 v[196:197], v[196:197], v[182:183]
	v_pk_add_f32 v[198:199], v[198:199], v[182:183]
	v_pk_add_f32 v[200:201], v[200:201], v[182:183]
	v_rcp_f32_e32 v194, v194
	v_rcp_f32_e32 v195, v195
	v_rcp_f32_e32 v196, v196
	v_rcp_f32_e32 v197, v197
	v_rcp_f32_e32 v198, v198
	v_rcp_f32_e32 v199, v199
	v_rcp_f32_e32 v200, v200
	v_rcp_f32_e32 v201, v201
	v_pk_mul_f32 v[186:187], v[186:187], v[194:195]
	v_pk_mul_f32 v[188:189], v[188:189], v[196:197]
	v_pk_mul_f32 v[190:191], v[190:191], v[198:199]
	v_pk_mul_f32 v[192:193], v[192:193], v[200:201]
	v_cvt_pk_f16_f32 v206, v186, v187
	v_cvt_pk_f16_f32 v207, v188, v189
	v_cvt_pk_f16_f32 v208, v190, v191
	v_cvt_pk_f16_f32 v209, v192, v193
	v_add_u32_e32 v185, 0x9000, v184
	global_store_dwordx4 v185, v[206:209], s[8:9]
	v_pk_mul_f32 v[186:187], v[92:93], v[176:177]
	v_pk_mul_f32 v[188:189], v[94:95], v[176:177]
	v_pk_mul_f32 v[190:191], v[88:89], v[176:177]
	v_pk_mul_f32 v[192:193], v[90:91], v[176:177]
	v_pk_mul_f32 v[194:195], v[186:187], v[178:179]
	v_pk_mul_f32 v[196:197], v[188:189], v[178:179]
	v_pk_mul_f32 v[198:199], v[190:191], v[178:179]
	v_pk_mul_f32 v[200:201], v[192:193], v[178:179]
	v_exp_f32_e32 v194, v194
	v_exp_f32_e32 v195, v195
	v_exp_f32_e32 v196, v196
	v_exp_f32_e32 v197, v197
	v_exp_f32_e32 v198, v198
	v_exp_f32_e32 v199, v199
	v_exp_f32_e32 v200, v200
	v_exp_f32_e32 v201, v201
	v_pk_add_f32 v[194:195], v[194:195], v[182:183]
	v_pk_add_f32 v[196:197], v[196:197], v[182:183]
	v_pk_add_f32 v[198:199], v[198:199], v[182:183]
	v_pk_add_f32 v[200:201], v[200:201], v[182:183]
	v_rcp_f32_e32 v194, v194
	v_rcp_f32_e32 v195, v195
	v_rcp_f32_e32 v196, v196
	v_rcp_f32_e32 v197, v197
	v_rcp_f32_e32 v198, v198
	v_rcp_f32_e32 v199, v199
	v_rcp_f32_e32 v200, v200
	v_rcp_f32_e32 v201, v201
	v_pk_mul_f32 v[186:187], v[186:187], v[194:195]
	v_pk_mul_f32 v[188:189], v[188:189], v[196:197]
	v_pk_mul_f32 v[190:191], v[190:191], v[198:199]
	v_pk_mul_f32 v[192:193], v[192:193], v[200:201]
	v_cvt_pk_f16_f32 v202, v186, v187
	v_cvt_pk_f16_f32 v203, v188, v189
	v_cvt_pk_f16_f32 v204, v190, v191
	v_cvt_pk_f16_f32 v205, v192, v193
	v_add_u32_e32 v185, 0x2000, v184
	global_store_dwordx4 v185, v[202:205], s[8:9]
	v_pk_mul_f32 v[186:187], v[84:85], v[176:177]
	v_pk_mul_f32 v[188:189], v[86:87], v[176:177]
	v_pk_mul_f32 v[190:191], v[80:81], v[176:177]
	v_pk_mul_f32 v[192:193], v[82:83], v[176:177]
	v_pk_mul_f32 v[194:195], v[186:187], v[178:179]
	v_pk_mul_f32 v[196:197], v[188:189], v[178:179]
	v_pk_mul_f32 v[198:199], v[190:191], v[178:179]
	v_pk_mul_f32 v[200:201], v[192:193], v[178:179]
	v_exp_f32_e32 v194, v194
	v_exp_f32_e32 v195, v195
	v_exp_f32_e32 v196, v196
	v_exp_f32_e32 v197, v197
	v_exp_f32_e32 v198, v198
	v_exp_f32_e32 v199, v199
	v_exp_f32_e32 v200, v200
	v_exp_f32_e32 v201, v201
	v_pk_add_f32 v[194:195], v[194:195], v[182:183]
	v_pk_add_f32 v[196:197], v[196:197], v[182:183]
	v_pk_add_f32 v[198:199], v[198:199], v[182:183]
	v_pk_add_f32 v[200:201], v[200:201], v[182:183]
	v_rcp_f32_e32 v194, v194
	v_rcp_f32_e32 v195, v195
	v_rcp_f32_e32 v196, v196
	v_rcp_f32_e32 v197, v197
	v_rcp_f32_e32 v198, v198
	v_rcp_f32_e32 v199, v199
	v_rcp_f32_e32 v200, v200
	v_rcp_f32_e32 v201, v201
	v_pk_mul_f32 v[186:187], v[186:187], v[194:195]
	v_pk_mul_f32 v[188:189], v[188:189], v[196:197]
	v_pk_mul_f32 v[190:191], v[190:191], v[198:199]
	v_pk_mul_f32 v[192:193], v[192:193], v[200:201]
	v_cvt_pk_f16_f32 v206, v186, v187
	v_cvt_pk_f16_f32 v207, v188, v189
	v_cvt_pk_f16_f32 v208, v190, v191
	v_cvt_pk_f16_f32 v209, v192, v193
	v_add_u32_e32 v185, 0xa000, v184
	global_store_dwordx4 v185, v[206:209], s[8:9]
	v_pk_mul_f32 v[186:187], v[76:77], v[176:177]
	v_pk_mul_f32 v[188:189], v[78:79], v[176:177]
	v_pk_mul_f32 v[190:191], v[72:73], v[176:177]
	v_pk_mul_f32 v[192:193], v[74:75], v[176:177]
	v_pk_mul_f32 v[194:195], v[186:187], v[178:179]
	v_pk_mul_f32 v[196:197], v[188:189], v[178:179]
	v_pk_mul_f32 v[198:199], v[190:191], v[178:179]
	v_pk_mul_f32 v[200:201], v[192:193], v[178:179]
	v_exp_f32_e32 v194, v194
	v_exp_f32_e32 v195, v195
	v_exp_f32_e32 v196, v196
	v_exp_f32_e32 v197, v197
	v_exp_f32_e32 v198, v198
	v_exp_f32_e32 v199, v199
	v_exp_f32_e32 v200, v200
	v_exp_f32_e32 v201, v201
	v_pk_add_f32 v[194:195], v[194:195], v[182:183]
	v_pk_add_f32 v[196:197], v[196:197], v[182:183]
	v_pk_add_f32 v[198:199], v[198:199], v[182:183]
	v_pk_add_f32 v[200:201], v[200:201], v[182:183]
	v_rcp_f32_e32 v194, v194
	v_rcp_f32_e32 v195, v195
	v_rcp_f32_e32 v196, v196
	v_rcp_f32_e32 v197, v197
	v_rcp_f32_e32 v198, v198
	v_rcp_f32_e32 v199, v199
	v_rcp_f32_e32 v200, v200
	v_rcp_f32_e32 v201, v201
	v_pk_mul_f32 v[186:187], v[186:187], v[194:195]
	v_pk_mul_f32 v[188:189], v[188:189], v[196:197]
	v_pk_mul_f32 v[190:191], v[190:191], v[198:199]
	v_pk_mul_f32 v[192:193], v[192:193], v[200:201]
	v_cvt_pk_f16_f32 v202, v186, v187
	v_cvt_pk_f16_f32 v203, v188, v189
	v_cvt_pk_f16_f32 v204, v190, v191
	v_cvt_pk_f16_f32 v205, v192, v193
	v_add_u32_e32 v185, 0x3000, v184
	global_store_dwordx4 v185, v[202:205], s[8:9]
	v_pk_mul_f32 v[186:187], v[68:69], v[176:177]
	v_pk_mul_f32 v[188:189], v[70:71], v[176:177]
	v_pk_mul_f32 v[190:191], v[64:65], v[176:177]
	v_pk_mul_f32 v[192:193], v[66:67], v[176:177]
	v_pk_mul_f32 v[194:195], v[186:187], v[178:179]
	v_pk_mul_f32 v[196:197], v[188:189], v[178:179]
	v_pk_mul_f32 v[198:199], v[190:191], v[178:179]
	v_pk_mul_f32 v[200:201], v[192:193], v[178:179]
	v_exp_f32_e32 v194, v194
	v_exp_f32_e32 v195, v195
	v_exp_f32_e32 v196, v196
	v_exp_f32_e32 v197, v197
	v_exp_f32_e32 v198, v198
	v_exp_f32_e32 v199, v199
	v_exp_f32_e32 v200, v200
	v_exp_f32_e32 v201, v201
	v_pk_add_f32 v[194:195], v[194:195], v[182:183]
	v_pk_add_f32 v[196:197], v[196:197], v[182:183]
	v_pk_add_f32 v[198:199], v[198:199], v[182:183]
	v_pk_add_f32 v[200:201], v[200:201], v[182:183]
	v_rcp_f32_e32 v194, v194
	v_rcp_f32_e32 v195, v195
	v_rcp_f32_e32 v196, v196
	v_rcp_f32_e32 v197, v197
	v_rcp_f32_e32 v198, v198
	v_rcp_f32_e32 v199, v199
	v_rcp_f32_e32 v200, v200
	v_rcp_f32_e32 v201, v201
	v_pk_mul_f32 v[186:187], v[186:187], v[194:195]
	v_pk_mul_f32 v[188:189], v[188:189], v[196:197]
	v_pk_mul_f32 v[190:191], v[190:191], v[198:199]
	v_pk_mul_f32 v[192:193], v[192:193], v[200:201]
	v_cvt_pk_f16_f32 v206, v186, v187
	v_cvt_pk_f16_f32 v207, v188, v189
	v_cvt_pk_f16_f32 v208, v190, v191
	v_cvt_pk_f16_f32 v209, v192, v193
	v_add_u32_e32 v185, 0xb000, v184
	global_store_dwordx4 v185, v[206:209], s[8:9]
	v_pk_mul_f32 v[186:187], v[60:61], v[176:177]
	v_pk_mul_f32 v[188:189], v[62:63], v[176:177]
	v_pk_mul_f32 v[190:191], v[56:57], v[176:177]
	v_pk_mul_f32 v[192:193], v[58:59], v[176:177]
	v_pk_mul_f32 v[194:195], v[186:187], v[178:179]
	v_pk_mul_f32 v[196:197], v[188:189], v[178:179]
	v_pk_mul_f32 v[198:199], v[190:191], v[178:179]
	v_pk_mul_f32 v[200:201], v[192:193], v[178:179]
	v_exp_f32_e32 v194, v194
	v_exp_f32_e32 v195, v195
	v_exp_f32_e32 v196, v196
	v_exp_f32_e32 v197, v197
	v_exp_f32_e32 v198, v198
	v_exp_f32_e32 v199, v199
	v_exp_f32_e32 v200, v200
	v_exp_f32_e32 v201, v201
	v_pk_add_f32 v[194:195], v[194:195], v[182:183]
	v_pk_add_f32 v[196:197], v[196:197], v[182:183]
	v_pk_add_f32 v[198:199], v[198:199], v[182:183]
	v_pk_add_f32 v[200:201], v[200:201], v[182:183]
	v_rcp_f32_e32 v194, v194
	v_rcp_f32_e32 v195, v195
	v_rcp_f32_e32 v196, v196
	v_rcp_f32_e32 v197, v197
	v_rcp_f32_e32 v198, v198
	v_rcp_f32_e32 v199, v199
	v_rcp_f32_e32 v200, v200
	v_rcp_f32_e32 v201, v201
	v_pk_mul_f32 v[186:187], v[186:187], v[194:195]
	v_pk_mul_f32 v[188:189], v[188:189], v[196:197]
	v_pk_mul_f32 v[190:191], v[190:191], v[198:199]
	v_pk_mul_f32 v[192:193], v[192:193], v[200:201]
	v_cvt_pk_f16_f32 v202, v186, v187
	v_cvt_pk_f16_f32 v203, v188, v189
	v_cvt_pk_f16_f32 v204, v190, v191
	v_cvt_pk_f16_f32 v205, v192, v193
	v_add_u32_e32 v185, 0x80000, v184
	global_store_dwordx4 v185, v[202:205], s[8:9]
	v_pk_mul_f32 v[186:187], v[52:53], v[176:177]
	v_pk_mul_f32 v[188:189], v[54:55], v[176:177]
	v_pk_mul_f32 v[190:191], v[48:49], v[176:177]
	v_pk_mul_f32 v[192:193], v[50:51], v[176:177]
	v_pk_mul_f32 v[194:195], v[186:187], v[178:179]
	v_pk_mul_f32 v[196:197], v[188:189], v[178:179]
	v_pk_mul_f32 v[198:199], v[190:191], v[178:179]
	v_pk_mul_f32 v[200:201], v[192:193], v[178:179]
	v_exp_f32_e32 v194, v194
	v_exp_f32_e32 v195, v195
	v_exp_f32_e32 v196, v196
	v_exp_f32_e32 v197, v197
	v_exp_f32_e32 v198, v198
	v_exp_f32_e32 v199, v199
	v_exp_f32_e32 v200, v200
	v_exp_f32_e32 v201, v201
	v_pk_add_f32 v[194:195], v[194:195], v[182:183]
	v_pk_add_f32 v[196:197], v[196:197], v[182:183]
	v_pk_add_f32 v[198:199], v[198:199], v[182:183]
	v_pk_add_f32 v[200:201], v[200:201], v[182:183]
	v_rcp_f32_e32 v194, v194
	v_rcp_f32_e32 v195, v195
	v_rcp_f32_e32 v196, v196
	v_rcp_f32_e32 v197, v197
	v_rcp_f32_e32 v198, v198
	v_rcp_f32_e32 v199, v199
	v_rcp_f32_e32 v200, v200
	v_rcp_f32_e32 v201, v201
	v_pk_mul_f32 v[186:187], v[186:187], v[194:195]
	v_pk_mul_f32 v[188:189], v[188:189], v[196:197]
	v_pk_mul_f32 v[190:191], v[190:191], v[198:199]
	v_pk_mul_f32 v[192:193], v[192:193], v[200:201]
	v_cvt_pk_f16_f32 v206, v186, v187
	v_cvt_pk_f16_f32 v207, v188, v189
	v_cvt_pk_f16_f32 v208, v190, v191
	v_cvt_pk_f16_f32 v209, v192, v193
	v_add_u32_e32 v185, 0x88000, v184
	global_store_dwordx4 v185, v[206:209], s[8:9]
	v_pk_mul_f32 v[186:187], v[44:45], v[176:177]
	v_pk_mul_f32 v[188:189], v[46:47], v[176:177]
	v_pk_mul_f32 v[190:191], v[40:41], v[176:177]
	v_pk_mul_f32 v[192:193], v[42:43], v[176:177]
	v_pk_mul_f32 v[194:195], v[186:187], v[178:179]
	v_pk_mul_f32 v[196:197], v[188:189], v[178:179]
	v_pk_mul_f32 v[198:199], v[190:191], v[178:179]
	v_pk_mul_f32 v[200:201], v[192:193], v[178:179]
	v_exp_f32_e32 v194, v194
	v_exp_f32_e32 v195, v195
	v_exp_f32_e32 v196, v196
	v_exp_f32_e32 v197, v197
	v_exp_f32_e32 v198, v198
	v_exp_f32_e32 v199, v199
	v_exp_f32_e32 v200, v200
	v_exp_f32_e32 v201, v201
	v_pk_add_f32 v[194:195], v[194:195], v[182:183]
	v_pk_add_f32 v[196:197], v[196:197], v[182:183]
	v_pk_add_f32 v[198:199], v[198:199], v[182:183]
	v_pk_add_f32 v[200:201], v[200:201], v[182:183]
	v_rcp_f32_e32 v194, v194
	v_rcp_f32_e32 v195, v195
	v_rcp_f32_e32 v196, v196
	v_rcp_f32_e32 v197, v197
	v_rcp_f32_e32 v198, v198
	v_rcp_f32_e32 v199, v199
	v_rcp_f32_e32 v200, v200
	v_rcp_f32_e32 v201, v201
	v_pk_mul_f32 v[186:187], v[186:187], v[194:195]
	v_pk_mul_f32 v[188:189], v[188:189], v[196:197]
	v_pk_mul_f32 v[190:191], v[190:191], v[198:199]
	v_pk_mul_f32 v[192:193], v[192:193], v[200:201]
	v_cvt_pk_f16_f32 v202, v186, v187
	v_cvt_pk_f16_f32 v203, v188, v189
	v_cvt_pk_f16_f32 v204, v190, v191
	v_cvt_pk_f16_f32 v205, v192, v193
	v_add_u32_e32 v185, 0x81000, v184
	global_store_dwordx4 v185, v[202:205], s[8:9]
	v_pk_mul_f32 v[186:187], v[36:37], v[176:177]
	v_pk_mul_f32 v[188:189], v[38:39], v[176:177]
	v_pk_mul_f32 v[190:191], v[32:33], v[176:177]
	v_pk_mul_f32 v[192:193], v[34:35], v[176:177]
	v_pk_mul_f32 v[194:195], v[186:187], v[178:179]
	v_pk_mul_f32 v[196:197], v[188:189], v[178:179]
	v_pk_mul_f32 v[198:199], v[190:191], v[178:179]
	v_pk_mul_f32 v[200:201], v[192:193], v[178:179]
	v_exp_f32_e32 v194, v194
	v_exp_f32_e32 v195, v195
	v_exp_f32_e32 v196, v196
	v_exp_f32_e32 v197, v197
	v_exp_f32_e32 v198, v198
	v_exp_f32_e32 v199, v199
	v_exp_f32_e32 v200, v200
	v_exp_f32_e32 v201, v201
	v_pk_add_f32 v[194:195], v[194:195], v[182:183]
	v_pk_add_f32 v[196:197], v[196:197], v[182:183]
	v_pk_add_f32 v[198:199], v[198:199], v[182:183]
	v_pk_add_f32 v[200:201], v[200:201], v[182:183]
	v_rcp_f32_e32 v194, v194
	v_rcp_f32_e32 v195, v195
	v_rcp_f32_e32 v196, v196
	v_rcp_f32_e32 v197, v197
	v_rcp_f32_e32 v198, v198
	v_rcp_f32_e32 v199, v199
	v_rcp_f32_e32 v200, v200
	v_rcp_f32_e32 v201, v201
	v_pk_mul_f32 v[186:187], v[186:187], v[194:195]
	v_pk_mul_f32 v[188:189], v[188:189], v[196:197]
	v_pk_mul_f32 v[190:191], v[190:191], v[198:199]
	v_pk_mul_f32 v[192:193], v[192:193], v[200:201]
	v_cvt_pk_f16_f32 v206, v186, v187
	v_cvt_pk_f16_f32 v207, v188, v189
	v_cvt_pk_f16_f32 v208, v190, v191
	v_cvt_pk_f16_f32 v209, v192, v193
	v_add_u32_e32 v185, 0x89000, v184
	global_store_dwordx4 v185, v[206:209], s[8:9]
	v_pk_mul_f32 v[186:187], v[28:29], v[176:177]
	v_pk_mul_f32 v[188:189], v[30:31], v[176:177]
	v_pk_mul_f32 v[190:191], v[24:25], v[176:177]
	v_pk_mul_f32 v[192:193], v[26:27], v[176:177]
	v_pk_mul_f32 v[194:195], v[186:187], v[178:179]
	v_pk_mul_f32 v[196:197], v[188:189], v[178:179]
	v_pk_mul_f32 v[198:199], v[190:191], v[178:179]
	v_pk_mul_f32 v[200:201], v[192:193], v[178:179]
	v_exp_f32_e32 v194, v194
	v_exp_f32_e32 v195, v195
	v_exp_f32_e32 v196, v196
	v_exp_f32_e32 v197, v197
	v_exp_f32_e32 v198, v198
	v_exp_f32_e32 v199, v199
	v_exp_f32_e32 v200, v200
	v_exp_f32_e32 v201, v201
	v_pk_add_f32 v[194:195], v[194:195], v[182:183]
	v_pk_add_f32 v[196:197], v[196:197], v[182:183]
	v_pk_add_f32 v[198:199], v[198:199], v[182:183]
	v_pk_add_f32 v[200:201], v[200:201], v[182:183]
	v_rcp_f32_e32 v194, v194
	v_rcp_f32_e32 v195, v195
	v_rcp_f32_e32 v196, v196
	v_rcp_f32_e32 v197, v197
	v_rcp_f32_e32 v198, v198
	v_rcp_f32_e32 v199, v199
	v_rcp_f32_e32 v200, v200
	v_rcp_f32_e32 v201, v201
	v_pk_mul_f32 v[186:187], v[186:187], v[194:195]
	v_pk_mul_f32 v[188:189], v[188:189], v[196:197]
	v_pk_mul_f32 v[190:191], v[190:191], v[198:199]
	v_pk_mul_f32 v[192:193], v[192:193], v[200:201]
	v_cvt_pk_f16_f32 v202, v186, v187
	v_cvt_pk_f16_f32 v203, v188, v189
	v_cvt_pk_f16_f32 v204, v190, v191
	v_cvt_pk_f16_f32 v205, v192, v193
	v_add_u32_e32 v185, 0x82000, v184
	global_store_dwordx4 v185, v[202:205], s[8:9]
	v_pk_mul_f32 v[186:187], v[20:21], v[176:177]
	v_pk_mul_f32 v[188:189], v[22:23], v[176:177]
	v_pk_mul_f32 v[190:191], v[16:17], v[176:177]
	v_pk_mul_f32 v[192:193], v[18:19], v[176:177]
	v_pk_mul_f32 v[194:195], v[186:187], v[178:179]
	v_pk_mul_f32 v[196:197], v[188:189], v[178:179]
	v_pk_mul_f32 v[198:199], v[190:191], v[178:179]
	v_pk_mul_f32 v[200:201], v[192:193], v[178:179]
	v_exp_f32_e32 v194, v194
	v_exp_f32_e32 v195, v195
	v_exp_f32_e32 v196, v196
	v_exp_f32_e32 v197, v197
	v_exp_f32_e32 v198, v198
	v_exp_f32_e32 v199, v199
	v_exp_f32_e32 v200, v200
	v_exp_f32_e32 v201, v201
	v_pk_add_f32 v[194:195], v[194:195], v[182:183]
	v_pk_add_f32 v[196:197], v[196:197], v[182:183]
	v_pk_add_f32 v[198:199], v[198:199], v[182:183]
	v_pk_add_f32 v[200:201], v[200:201], v[182:183]
	v_rcp_f32_e32 v194, v194
	v_rcp_f32_e32 v195, v195
	v_rcp_f32_e32 v196, v196
	v_rcp_f32_e32 v197, v197
	v_rcp_f32_e32 v198, v198
	v_rcp_f32_e32 v199, v199
	v_rcp_f32_e32 v200, v200
	v_rcp_f32_e32 v201, v201
	v_pk_mul_f32 v[186:187], v[186:187], v[194:195]
	v_pk_mul_f32 v[188:189], v[188:189], v[196:197]
	v_pk_mul_f32 v[190:191], v[190:191], v[198:199]
	v_pk_mul_f32 v[192:193], v[192:193], v[200:201]
	v_cvt_pk_f16_f32 v206, v186, v187
	v_cvt_pk_f16_f32 v207, v188, v189
	v_cvt_pk_f16_f32 v208, v190, v191
	v_cvt_pk_f16_f32 v209, v192, v193
	v_add_u32_e32 v185, 0x8a000, v184
	global_store_dwordx4 v185, v[206:209], s[8:9]
	v_pk_mul_f32 v[186:187], v[12:13], v[176:177]
	v_pk_mul_f32 v[188:189], v[14:15], v[176:177]
	v_pk_mul_f32 v[190:191], v[8:9], v[176:177]
	v_pk_mul_f32 v[192:193], v[10:11], v[176:177]
	v_pk_mul_f32 v[194:195], v[186:187], v[178:179]
	v_pk_mul_f32 v[196:197], v[188:189], v[178:179]
	v_pk_mul_f32 v[198:199], v[190:191], v[178:179]
	v_pk_mul_f32 v[200:201], v[192:193], v[178:179]
	v_exp_f32_e32 v194, v194
	v_exp_f32_e32 v195, v195
	v_exp_f32_e32 v196, v196
	v_exp_f32_e32 v197, v197
	v_exp_f32_e32 v198, v198
	v_exp_f32_e32 v199, v199
	v_exp_f32_e32 v200, v200
	v_exp_f32_e32 v201, v201
	v_pk_add_f32 v[194:195], v[194:195], v[182:183]
	v_pk_add_f32 v[196:197], v[196:197], v[182:183]
	v_pk_add_f32 v[198:199], v[198:199], v[182:183]
	v_pk_add_f32 v[200:201], v[200:201], v[182:183]
	v_rcp_f32_e32 v194, v194
	v_rcp_f32_e32 v195, v195
	v_rcp_f32_e32 v196, v196
	v_rcp_f32_e32 v197, v197
	v_rcp_f32_e32 v198, v198
	v_rcp_f32_e32 v199, v199
	v_rcp_f32_e32 v200, v200
	v_rcp_f32_e32 v201, v201
	v_pk_mul_f32 v[186:187], v[186:187], v[194:195]
	v_pk_mul_f32 v[188:189], v[188:189], v[196:197]
	v_pk_mul_f32 v[190:191], v[190:191], v[198:199]
	v_pk_mul_f32 v[192:193], v[192:193], v[200:201]
	v_cvt_pk_f16_f32 v202, v186, v187
	v_cvt_pk_f16_f32 v203, v188, v189
	v_cvt_pk_f16_f32 v204, v190, v191
	v_cvt_pk_f16_f32 v205, v192, v193
	v_add_u32_e32 v185, 0x83000, v184
	global_store_dwordx4 v185, v[202:205], s[8:9]
	v_pk_mul_f32 v[186:187], v[4:5], v[176:177]
	v_pk_mul_f32 v[188:189], v[6:7], v[176:177]
	v_pk_mul_f32 v[190:191], v[0:1], v[176:177]
	v_pk_mul_f32 v[192:193], v[2:3], v[176:177]
	v_pk_mul_f32 v[194:195], v[186:187], v[178:179]
	v_pk_mul_f32 v[196:197], v[188:189], v[178:179]
	v_pk_mul_f32 v[198:199], v[190:191], v[178:179]
	v_pk_mul_f32 v[200:201], v[192:193], v[178:179]
	v_exp_f32_e32 v194, v194
	v_exp_f32_e32 v195, v195
	v_exp_f32_e32 v196, v196
	v_exp_f32_e32 v197, v197
	v_exp_f32_e32 v198, v198
	v_exp_f32_e32 v199, v199
	v_exp_f32_e32 v200, v200
	v_exp_f32_e32 v201, v201
	v_pk_add_f32 v[194:195], v[194:195], v[182:183]
	v_pk_add_f32 v[196:197], v[196:197], v[182:183]
	v_pk_add_f32 v[198:199], v[198:199], v[182:183]
	v_pk_add_f32 v[200:201], v[200:201], v[182:183]
	v_rcp_f32_e32 v194, v194
	v_rcp_f32_e32 v195, v195
	v_rcp_f32_e32 v196, v196
	v_rcp_f32_e32 v197, v197
	v_rcp_f32_e32 v198, v198
	v_rcp_f32_e32 v199, v199
	v_rcp_f32_e32 v200, v200
	v_rcp_f32_e32 v201, v201
	v_pk_mul_f32 v[186:187], v[186:187], v[194:195]
	v_pk_mul_f32 v[188:189], v[188:189], v[196:197]
	v_pk_mul_f32 v[190:191], v[190:191], v[198:199]
	v_pk_mul_f32 v[192:193], v[192:193], v[200:201]
	v_cvt_pk_f16_f32 v206, v186, v187
	v_cvt_pk_f16_f32 v207, v188, v189
	v_cvt_pk_f16_f32 v208, v190, v191
	v_cvt_pk_f16_f32 v209, v192, v193
	v_add_u32_e32 v185, 0x8b000, v184
	global_store_dwordx4 v185, v[206:209], s[8:9]
	s_branch .LBB0_568

.LBB0_604:
	s_cmp_eq_u32 s20, 60
	s_cbranch_scc1 .Lepz_b_old
	s_mov_b32 s5, 13
	s_mov_b32 s10, 0x18b00000
	s_mov_b32 s11, 44
	s_mov_b32 s87, 0
	s_cmp_lt_u32 s20, 44
	s_cselect_b32 s5, 12, s5
	s_cselect_b32 s10, 0x16b00000, s10
	s_cselect_b32 s11, 36, s11
	s_cselect_b32 s87, 2, s87
	s_cmp_lt_u32 s20, 36
	s_cselect_b32 s5, 10, s5
	s_cselect_b32 s10, 0x16300000, s10
	s_cselect_b32 s11, 34, s11
	s_cselect_b32 s87, 1, s87
	s_cmp_lt_u32 s20, 34
	s_cselect_b32 s5, 10, s5
	s_cselect_b32 s10, 0x15b00000, s10
	s_cselect_b32 s11, 32, s11
	s_cselect_b32 s87, 0, s87
	s_cmp_lt_u32 s20, 32
	s_cselect_b32 s5, 12, s5
	s_cselect_b32 s10, 0x13b00000, s10
	s_cselect_b32 s11, 24, s11
	s_cselect_b32 s87, 0, s87
	s_cmp_lt_u32 s20, 24
	s_cselect_b32 s5, 8, s5
	s_cselect_b32 s10, 0x11b00000, s10
	s_cselect_b32 s11, 16, s11
	s_cselect_b32 s87, 2, s87
	s_cselect_b32 s52, 1, 0
	s_lshl_b32 s89, 0x80, s5
	s_lshl_b32 s39, 16, s5
	s_add_i32 s47, s5, 8
	s_movk_i32 s95, 0x100
	s_cmp_lg_u32 s52, 0
	s_cselect_b32 s94, 0x80000, s89
	s_cselect_b32 s95, 0x8000, s95
	s_cselect_b32 s46, 16, 9
	s_cselect_b32 s47, 20, s47
	s_sub_i32 s11, s20, s11
	s_lshl_b32 s11, s11, s46
	s_lshl_b32 s47, s4, s47
	s_add_u32 s10, s10, s11
	s_add_u32 s10, s10, s47
	s_add_u32 s8, s70, s10
	s_addc_u32 s9, s71, 0
	v_and_b32_e32 v184, 15, v222
	v_add_u32_e32 v184, s25, v184
	v_lshlrev_b32_e32 v184, s5, v184
	v_lshrrev_b32_e32 v185, 4, v222
	v_lshlrev_b32_e32 v185, 4, v185
	s_lshl_b32 s53, s33, 1
	v_add3_u32 v184, v184, v185, s53
	s_mov_b32 s89, 0
	s_cmp_eq_u32 s87, 2
	s_cbranch_scc1 .Lepz_b_silu
	s_cmp_eq_u32 s87, 1
	s_cbranch_scc1 .Lepz_b_bf
	v_cvt_pk_f16_f32 v202, v124, v125
	v_cvt_pk_f16_f32 v203, v126, v127
	v_cvt_pk_f16_f32 v204, v120, v121
	v_cvt_pk_f16_f32 v205, v122, v123
	v_add_u32_e32 v185, s89, v184
	global_store_dwordx4 v185, v[202:205], s[8:9]
	v_cvt_pk_f16_f32 v206, v116, v117
	v_cvt_pk_f16_f32 v207, v118, v119
	v_cvt_pk_f16_f32 v208, v112, v113
	v_cvt_pk_f16_f32 v209, v114, v115
	s_add_u32 s53, s89, s95
	v_add_u32_e32 v185, s53, v184
	global_store_dwordx4 v185, v[206:209], s[8:9]
	s_add_u32 s89, s89, s39
	v_cvt_pk_f16_f32 v202, v108, v109
	v_cvt_pk_f16_f32 v203, v110, v111
	v_cvt_pk_f16_f32 v204, v104, v105
	v_cvt_pk_f16_f32 v205, v106, v107
	v_add_u32_e32 v185, s89, v184
	global_store_dwordx4 v185, v[202:205], s[8:9]
	v_cvt_pk_f16_f32 v206, v100, v101
	v_cvt_pk_f16_f32 v207, v102, v103
	v_cvt_pk_f16_f32 v208, v96, v97
	v_cvt_pk_f16_f32 v209, v98, v99
	s_add_u32 s53, s89, s95
	v_add_u32_e32 v185, s53, v184
	global_store_dwordx4 v185, v[206:209], s[8:9]
	s_add_u32 s89, s89, s39
	v_cvt_pk_f16_f32 v202, v92, v93
	v_cvt_pk_f16_f32 v203, v94, v95
	v_cvt_pk_f16_f32 v204, v88, v89
	v_cvt_pk_f16_f32 v205, v90, v91
	v_add_u32_e32 v185, s89, v184
	global_store_dwordx4 v185, v[202:205], s[8:9]
	v_cvt_pk_f16_f32 v206, v84, v85
	v_cvt_pk_f16_f32 v207, v86, v87
	v_cvt_pk_f16_f32 v208, v80, v81
	v_cvt_pk_f16_f32 v209, v82, v83
	s_add_u32 s53, s89, s95
	v_add_u32_e32 v185, s53, v184
	global_store_dwordx4 v185, v[206:209], s[8:9]
	s_add_u32 s89, s89, s39
	v_cvt_pk_f16_f32 v202, v76, v77
	v_cvt_pk_f16_f32 v203, v78, v79
	v_cvt_pk_f16_f32 v204, v72, v73
	v_cvt_pk_f16_f32 v205, v74, v75
	v_add_u32_e32 v185, s89, v184
	global_store_dwordx4 v185, v[202:205], s[8:9]
	v_cvt_pk_f16_f32 v206, v68, v69
	v_cvt_pk_f16_f32 v207, v70, v71
	v_cvt_pk_f16_f32 v208, v64, v65
	v_cvt_pk_f16_f32 v209, v66, v67
	s_add_u32 s53, s89, s95
	v_add_u32_e32 v185, s53, v184
	global_store_dwordx4 v185, v[206:209], s[8:9]
	s_mov_b32 s89, s94
	v_cvt_pk_f16_f32 v202, v60, v61
	v_cvt_pk_f16_f32 v203, v62, v63
	v_cvt_pk_f16_f32 v204, v56, v57
	v_cvt_pk_f16_f32 v205, v58, v59
	v_add_u32_e32 v185, s89, v184
	global_store_dwordx4 v185, v[202:205], s[8:9]
	v_cvt_pk_f16_f32 v206, v52, v53
	v_cvt_pk_f16_f32 v207, v54, v55
	v_cvt_pk_f16_f32 v208, v48, v49
	v_cvt_pk_f16_f32 v209, v50, v51
	s_add_u32 s53, s89, s95
	v_add_u32_e32 v185, s53, v184
	global_store_dwordx4 v185, v[206:209], s[8:9]
	s_add_u32 s89, s89, s39
	v_cvt_pk_f16_f32 v202, v44, v45
	v_cvt_pk_f16_f32 v203, v46, v47
	v_cvt_pk_f16_f32 v204, v40, v41
	v_cvt_pk_f16_f32 v205, v42, v43
	v_add_u32_e32 v185, s89, v184
	global_store_dwordx4 v185, v[202:205], s[8:9]
	v_cvt_pk_f16_f32 v206, v36, v37
	v_cvt_pk_f16_f32 v207, v38, v39
	v_cvt_pk_f16_f32 v208, v32, v33
	v_cvt_pk_f16_f32 v209, v34, v35
	s_add_u32 s53, s89, s95
	v_add_u32_e32 v185, s53, v184
	global_store_dwordx4 v185, v[206:209], s[8:9]
	s_add_u32 s89, s89, s39
	v_cvt_pk_f16_f32 v202, v28, v29
	v_cvt_pk_f16_f32 v203, v30, v31
	v_cvt_pk_f16_f32 v204, v24, v25
	v_cvt_pk_f16_f32 v205, v26, v27
	v_add_u32_e32 v185, s89, v184
	global_store_dwordx4 v185, v[202:205], s[8:9]
	v_cvt_pk_f16_f32 v206, v20, v21
	v_cvt_pk_f16_f32 v207, v22, v23
	v_cvt_pk_f16_f32 v208, v16, v17
	v_cvt_pk_f16_f32 v209, v18, v19
	s_add_u32 s53, s89, s95
	v_add_u32_e32 v185, s53, v184
	global_store_dwordx4 v185, v[206:209], s[8:9]
	s_add_u32 s89, s89, s39
	v_cvt_pk_f16_f32 v202, v12, v13
	v_cvt_pk_f16_f32 v203, v14, v15
	v_cvt_pk_f16_f32 v204, v8, v9
	v_cvt_pk_f16_f32 v205, v10, v11
	v_add_u32_e32 v185, s89, v184
	global_store_dwordx4 v185, v[202:205], s[8:9]
	v_cvt_pk_f16_f32 v206, v4, v5
	v_cvt_pk_f16_f32 v207, v6, v7
	v_cvt_pk_f16_f32 v208, v0, v1
	v_cvt_pk_f16_f32 v209, v2, v3
	s_add_u32 s53, s89, s95
	v_add_u32_e32 v185, s53, v184
	global_store_dwordx4 v185, v[206:209], s[8:9]
	s_branch .LBB0_993
.Lepz_b_bf:
	v_cvt_pk_bf16_f32 v202, v124, v125
	v_cvt_pk_bf16_f32 v203, v126, v127
	v_cvt_pk_bf16_f32 v204, v120, v121
	v_cvt_pk_bf16_f32 v205, v122, v123
	v_add_u32_e32 v185, s89, v184
	global_store_dwordx4 v185, v[202:205], s[8:9]
	v_cvt_pk_bf16_f32 v206, v116, v117
	v_cvt_pk_bf16_f32 v207, v118, v119
	v_cvt_pk_bf16_f32 v208, v112, v113
	v_cvt_pk_bf16_f32 v209, v114, v115
	s_add_u32 s53, s89, s95
	v_add_u32_e32 v185, s53, v184
	global_store_dwordx4 v185, v[206:209], s[8:9]
	s_add_u32 s89, s89, s39
	v_cvt_pk_bf16_f32 v202, v108, v109
	v_cvt_pk_bf16_f32 v203, v110, v111
	v_cvt_pk_bf16_f32 v204, v104, v105
	v_cvt_pk_bf16_f32 v205, v106, v107
	v_add_u32_e32 v185, s89, v184
	global_store_dwordx4 v185, v[202:205], s[8:9]
	v_cvt_pk_bf16_f32 v206, v100, v101
	v_cvt_pk_bf16_f32 v207, v102, v103
	v_cvt_pk_bf16_f32 v208, v96, v97
	v_cvt_pk_bf16_f32 v209, v98, v99
	s_add_u32 s53, s89, s95
	v_add_u32_e32 v185, s53, v184
	global_store_dwordx4 v185, v[206:209], s[8:9]
	s_add_u32 s89, s89, s39
	v_cvt_pk_bf16_f32 v202, v92, v93
	v_cvt_pk_bf16_f32 v203, v94, v95
	v_cvt_pk_bf16_f32 v204, v88, v89
	v_cvt_pk_bf16_f32 v205, v90, v91
	v_add_u32_e32 v185, s89, v184
	global_store_dwordx4 v185, v[202:205], s[8:9]
	v_cvt_pk_bf16_f32 v206, v84, v85
	v_cvt_pk_bf16_f32 v207, v86, v87
	v_cvt_pk_bf16_f32 v208, v80, v81
	v_cvt_pk_bf16_f32 v209, v82, v83
	s_add_u32 s53, s89, s95
	v_add_u32_e32 v185, s53, v184
	global_store_dwordx4 v185, v[206:209], s[8:9]
	s_add_u32 s89, s89, s39
	v_cvt_pk_bf16_f32 v202, v76, v77
	v_cvt_pk_bf16_f32 v203, v78, v79
	v_cvt_pk_bf16_f32 v204, v72, v73
	v_cvt_pk_bf16_f32 v205, v74, v75
	v_add_u32_e32 v185, s89, v184
	global_store_dwordx4 v185, v[202:205], s[8:9]
	v_cvt_pk_bf16_f32 v206, v68, v69
	v_cvt_pk_bf16_f32 v207, v70, v71
	v_cvt_pk_bf16_f32 v208, v64, v65
	v_cvt_pk_bf16_f32 v209, v66, v67
	s_add_u32 s53, s89, s95
	v_add_u32_e32 v185, s53, v184
	global_store_dwordx4 v185, v[206:209], s[8:9]
	s_mov_b32 s89, s94
	v_cvt_pk_bf16_f32 v202, v60, v61
	v_cvt_pk_bf16_f32 v203, v62, v63
	v_cvt_pk_bf16_f32 v204, v56, v57
	v_cvt_pk_bf16_f32 v205, v58, v59
	v_add_u32_e32 v185, s89, v184
	global_store_dwordx4 v185, v[202:205], s[8:9]
	v_cvt_pk_bf16_f32 v206, v52, v53
	v_cvt_pk_bf16_f32 v207, v54, v55
	v_cvt_pk_bf16_f32 v208, v48, v49
	v_cvt_pk_bf16_f32 v209, v50, v51
	s_add_u32 s53, s89, s95
	v_add_u32_e32 v185, s53, v184
	global_store_dwordx4 v185, v[206:209], s[8:9]
	s_add_u32 s89, s89, s39
	v_cvt_pk_bf16_f32 v202, v44, v45
	v_cvt_pk_bf16_f32 v203, v46, v47
	v_cvt_pk_bf16_f32 v204, v40, v41
	v_cvt_pk_bf16_f32 v205, v42, v43
	v_add_u32_e32 v185, s89, v184
	global_store_dwordx4 v185, v[202:205], s[8:9]
	v_cvt_pk_bf16_f32 v206, v36, v37
	v_cvt_pk_bf16_f32 v207, v38, v39
	v_cvt_pk_bf16_f32 v208, v32, v33
	v_cvt_pk_bf16_f32 v209, v34, v35
	s_add_u32 s53, s89, s95
	v_add_u32_e32 v185, s53, v184
	global_store_dwordx4 v185, v[206:209], s[8:9]
	s_add_u32 s89, s89, s39
	v_cvt_pk_bf16_f32 v202, v28, v29
	v_cvt_pk_bf16_f32 v203, v30, v31
	v_cvt_pk_bf16_f32 v204, v24, v25
	v_cvt_pk_bf16_f32 v205, v26, v27
	v_add_u32_e32 v185, s89, v184
	global_store_dwordx4 v185, v[202:205], s[8:9]
	v_cvt_pk_bf16_f32 v206, v20, v21
	v_cvt_pk_bf16_f32 v207, v22, v23
	v_cvt_pk_bf16_f32 v208, v16, v17
	v_cvt_pk_bf16_f32 v209, v18, v19
	s_add_u32 s53, s89, s95
	v_add_u32_e32 v185, s53, v184
	global_store_dwordx4 v185, v[206:209], s[8:9]
	s_add_u32 s89, s89, s39
	v_cvt_pk_bf16_f32 v202, v12, v13
	v_cvt_pk_bf16_f32 v203, v14, v15
	v_cvt_pk_bf16_f32 v204, v8, v9
	v_cvt_pk_bf16_f32 v205, v10, v11
	v_add_u32_e32 v185, s89, v184
	global_store_dwordx4 v185, v[202:205], s[8:9]
	v_cvt_pk_bf16_f32 v206, v4, v5
	v_cvt_pk_bf16_f32 v207, v6, v7
	v_cvt_pk_bf16_f32 v208, v0, v1
	v_cvt_pk_bf16_f32 v209, v2, v3
	s_add_u32 s53, s89, s95
	v_add_u32_e32 v185, s53, v184
	global_store_dwordx4 v185, v[206:209], s[8:9]
	s_branch .LBB0_993
.Lepz_b_silu:
	v_mov_b32_e32 v178, 0xbfb8aa3b
	v_mov_b32_e32 v179, 0xbfb8aa3b
	v_mov_b32_e32 v182, 1.0
	v_mov_b32_e32 v183, 1.0
	v_pk_mul_f32 v[194:195], v[124:125], v[178:179]
	v_pk_mul_f32 v[196:197], v[126:127], v[178:179]
	v_pk_mul_f32 v[198:199], v[120:121], v[178:179]
	v_pk_mul_f32 v[200:201], v[122:123], v[178:179]
	v_exp_f32_e32 v194, v194
	v_exp_f32_e32 v195, v195
	v_exp_f32_e32 v196, v196
	v_exp_f32_e32 v197, v197
	v_exp_f32_e32 v198, v198
	v_exp_f32_e32 v199, v199
	v_exp_f32_e32 v200, v200
	v_exp_f32_e32 v201, v201
	v_pk_add_f32 v[194:195], v[194:195], v[182:183]
	v_pk_add_f32 v[196:197], v[196:197], v[182:183]
	v_pk_add_f32 v[198:199], v[198:199], v[182:183]
	v_pk_add_f32 v[200:201], v[200:201], v[182:183]
	v_rcp_f32_e32 v194, v194
	v_rcp_f32_e32 v195, v195
	v_rcp_f32_e32 v196, v196
	v_rcp_f32_e32 v197, v197
	v_rcp_f32_e32 v198, v198
	v_rcp_f32_e32 v199, v199
	v_rcp_f32_e32 v200, v200
	v_rcp_f32_e32 v201, v201
	v_pk_mul_f32 v[186:187], v[124:125], v[194:195]
	v_pk_mul_f32 v[188:189], v[126:127], v[196:197]
	v_pk_mul_f32 v[190:191], v[120:121], v[198:199]
	v_pk_mul_f32 v[192:193], v[122:123], v[200:201]
	v_cvt_pk_f16_f32 v202, v186, v187
	v_cvt_pk_f16_f32 v203, v188, v189
	v_cvt_pk_f16_f32 v204, v190, v191
	v_cvt_pk_f16_f32 v205, v192, v193
	v_add_u32_e32 v185, s89, v184
	global_store_dwordx4 v185, v[202:205], s[8:9]
	v_pk_mul_f32 v[194:195], v[116:117], v[178:179]
	v_pk_mul_f32 v[196:197], v[118:119], v[178:179]
	v_pk_mul_f32 v[198:199], v[112:113], v[178:179]
	v_pk_mul_f32 v[200:201], v[114:115], v[178:179]
	v_exp_f32_e32 v194, v194
	v_exp_f32_e32 v195, v195
	v_exp_f32_e32 v196, v196
	v_exp_f32_e32 v197, v197
	v_exp_f32_e32 v198, v198
	v_exp_f32_e32 v199, v199
	v_exp_f32_e32 v200, v200
	v_exp_f32_e32 v201, v201
	v_pk_add_f32 v[194:195], v[194:195], v[182:183]
	v_pk_add_f32 v[196:197], v[196:197], v[182:183]
	v_pk_add_f32 v[198:199], v[198:199], v[182:183]
	v_pk_add_f32 v[200:201], v[200:201], v[182:183]
	v_rcp_f32_e32 v194, v194
	v_rcp_f32_e32 v195, v195
	v_rcp_f32_e32 v196, v196
	v_rcp_f32_e32 v197, v197
	v_rcp_f32_e32 v198, v198
	v_rcp_f32_e32 v199, v199
	v_rcp_f32_e32 v200, v200
	v_rcp_f32_e32 v201, v201
	v_pk_mul_f32 v[186:187], v[116:117], v[194:195]
	v_pk_mul_f32 v[188:189], v[118:119], v[196:197]
	v_pk_mul_f32 v[190:191], v[112:113], v[198:199]
	v_pk_mul_f32 v[192:193], v[114:115], v[200:201]
	v_cvt_pk_f16_f32 v206, v186, v187
	v_cvt_pk_f16_f32 v207, v188, v189
	v_cvt_pk_f16_f32 v208, v190, v191
	v_cvt_pk_f16_f32 v209, v192, v193
	s_add_u32 s53, s89, s95
	v_add_u32_e32 v185, s53, v184
	global_store_dwordx4 v185, v[206:209], s[8:9]
	s_add_u32 s89, s89, s39
	v_pk_mul_f32 v[194:195], v[108:109], v[178:179]
	v_pk_mul_f32 v[196:197], v[110:111], v[178:179]
	v_pk_mul_f32 v[198:199], v[104:105], v[178:179]
	v_pk_mul_f32 v[200:201], v[106:107], v[178:179]
	v_exp_f32_e32 v194, v194
	v_exp_f32_e32 v195, v195
	v_exp_f32_e32 v196, v196
	v_exp_f32_e32 v197, v197
	v_exp_f32_e32 v198, v198
	v_exp_f32_e32 v199, v199
	v_exp_f32_e32 v200, v200
	v_exp_f32_e32 v201, v201
	v_pk_add_f32 v[194:195], v[194:195], v[182:183]
	v_pk_add_f32 v[196:197], v[196:197], v[182:183]
	v_pk_add_f32 v[198:199], v[198:199], v[182:183]
	v_pk_add_f32 v[200:201], v[200:201], v[182:183]
	v_rcp_f32_e32 v194, v194
	v_rcp_f32_e32 v195, v195
	v_rcp_f32_e32 v196, v196
	v_rcp_f32_e32 v197, v197
	v_rcp_f32_e32 v198, v198
	v_rcp_f32_e32 v199, v199
	v_rcp_f32_e32 v200, v200
	v_rcp_f32_e32 v201, v201
	v_pk_mul_f32 v[186:187], v[108:109], v[194:195]
	v_pk_mul_f32 v[188:189], v[110:111], v[196:197]
	v_pk_mul_f32 v[190:191], v[104:105], v[198:199]
	v_pk_mul_f32 v[192:193], v[106:107], v[200:201]
	v_cvt_pk_f16_f32 v202, v186, v187
	v_cvt_pk_f16_f32 v203, v188, v189
	v_cvt_pk_f16_f32 v204, v190, v191
	v_cvt_pk_f16_f32 v205, v192, v193
	v_add_u32_e32 v185, s89, v184
	global_store_dwordx4 v185, v[202:205], s[8:9]
	v_pk_mul_f32 v[194:195], v[100:101], v[178:179]
	v_pk_mul_f32 v[196:197], v[102:103], v[178:179]
	v_pk_mul_f32 v[198:199], v[96:97], v[178:179]
	v_pk_mul_f32 v[200:201], v[98:99], v[178:179]
	v_exp_f32_e32 v194, v194
	v_exp_f32_e32 v195, v195
	v_exp_f32_e32 v196, v196
	v_exp_f32_e32 v197, v197
	v_exp_f32_e32 v198, v198
	v_exp_f32_e32 v199, v199
	v_exp_f32_e32 v200, v200
	v_exp_f32_e32 v201, v201
	v_pk_add_f32 v[194:195], v[194:195], v[182:183]
	v_pk_add_f32 v[196:197], v[196:197], v[182:183]
	v_pk_add_f32 v[198:199], v[198:199], v[182:183]
	v_pk_add_f32 v[200:201], v[200:201], v[182:183]
	v_rcp_f32_e32 v194, v194
	v_rcp_f32_e32 v195, v195
	v_rcp_f32_e32 v196, v196
	v_rcp_f32_e32 v197, v197
	v_rcp_f32_e32 v198, v198
	v_rcp_f32_e32 v199, v199
	v_rcp_f32_e32 v200, v200
	v_rcp_f32_e32 v201, v201
	v_pk_mul_f32 v[186:187], v[100:101], v[194:195]
	v_pk_mul_f32 v[188:189], v[102:103], v[196:197]
	v_pk_mul_f32 v[190:191], v[96:97], v[198:199]
	v_pk_mul_f32 v[192:193], v[98:99], v[200:201]
	v_cvt_pk_f16_f32 v206, v186, v187
	v_cvt_pk_f16_f32 v207, v188, v189
	v_cvt_pk_f16_f32 v208, v190, v191
	v_cvt_pk_f16_f32 v209, v192, v193
	s_add_u32 s53, s89, s95
	v_add_u32_e32 v185, s53, v184
	global_store_dwordx4 v185, v[206:209], s[8:9]
	s_add_u32 s89, s89, s39
	v_pk_mul_f32 v[194:195], v[92:93], v[178:179]
	v_pk_mul_f32 v[196:197], v[94:95], v[178:179]
	v_pk_mul_f32 v[198:199], v[88:89], v[178:179]
	v_pk_mul_f32 v[200:201], v[90:91], v[178:179]
	v_exp_f32_e32 v194, v194
	v_exp_f32_e32 v195, v195
	v_exp_f32_e32 v196, v196
	v_exp_f32_e32 v197, v197
	v_exp_f32_e32 v198, v198
	v_exp_f32_e32 v199, v199
	v_exp_f32_e32 v200, v200
	v_exp_f32_e32 v201, v201
	v_pk_add_f32 v[194:195], v[194:195], v[182:183]
	v_pk_add_f32 v[196:197], v[196:197], v[182:183]
	v_pk_add_f32 v[198:199], v[198:199], v[182:183]
	v_pk_add_f32 v[200:201], v[200:201], v[182:183]
	v_rcp_f32_e32 v194, v194
	v_rcp_f32_e32 v195, v195
	v_rcp_f32_e32 v196, v196
	v_rcp_f32_e32 v197, v197
	v_rcp_f32_e32 v198, v198
	v_rcp_f32_e32 v199, v199
	v_rcp_f32_e32 v200, v200
	v_rcp_f32_e32 v201, v201
	v_pk_mul_f32 v[186:187], v[92:93], v[194:195]
	v_pk_mul_f32 v[188:189], v[94:95], v[196:197]
	v_pk_mul_f32 v[190:191], v[88:89], v[198:199]
	v_pk_mul_f32 v[192:193], v[90:91], v[200:201]
	v_cvt_pk_f16_f32 v202, v186, v187
	v_cvt_pk_f16_f32 v203, v188, v189
	v_cvt_pk_f16_f32 v204, v190, v191
	v_cvt_pk_f16_f32 v205, v192, v193
	v_add_u32_e32 v185, s89, v184
	global_store_dwordx4 v185, v[202:205], s[8:9]
	v_pk_mul_f32 v[194:195], v[84:85], v[178:179]
	v_pk_mul_f32 v[196:197], v[86:87], v[178:179]
	v_pk_mul_f32 v[198:199], v[80:81], v[178:179]
	v_pk_mul_f32 v[200:201], v[82:83], v[178:179]
	v_exp_f32_e32 v194, v194
	v_exp_f32_e32 v195, v195
	v_exp_f32_e32 v196, v196
	v_exp_f32_e32 v197, v197
	v_exp_f32_e32 v198, v198
	v_exp_f32_e32 v199, v199
	v_exp_f32_e32 v200, v200
	v_exp_f32_e32 v201, v201
	v_pk_add_f32 v[194:195], v[194:195], v[182:183]
	v_pk_add_f32 v[196:197], v[196:197], v[182:183]
	v_pk_add_f32 v[198:199], v[198:199], v[182:183]
	v_pk_add_f32 v[200:201], v[200:201], v[182:183]
	v_rcp_f32_e32 v194, v194
	v_rcp_f32_e32 v195, v195
	v_rcp_f32_e32 v196, v196
	v_rcp_f32_e32 v197, v197
	v_rcp_f32_e32 v198, v198
	v_rcp_f32_e32 v199, v199
	v_rcp_f32_e32 v200, v200
	v_rcp_f32_e32 v201, v201
	v_pk_mul_f32 v[186:187], v[84:85], v[194:195]
	v_pk_mul_f32 v[188:189], v[86:87], v[196:197]
	v_pk_mul_f32 v[190:191], v[80:81], v[198:199]
	v_pk_mul_f32 v[192:193], v[82:83], v[200:201]
	v_cvt_pk_f16_f32 v206, v186, v187
	v_cvt_pk_f16_f32 v207, v188, v189
	v_cvt_pk_f16_f32 v208, v190, v191
	v_cvt_pk_f16_f32 v209, v192, v193
	s_add_u32 s53, s89, s95
	v_add_u32_e32 v185, s53, v184
	global_store_dwordx4 v185, v[206:209], s[8:9]
	s_add_u32 s89, s89, s39
	v_pk_mul_f32 v[194:195], v[76:77], v[178:179]
	v_pk_mul_f32 v[196:197], v[78:79], v[178:179]
	v_pk_mul_f32 v[198:199], v[72:73], v[178:179]
	v_pk_mul_f32 v[200:201], v[74:75], v[178:179]
	v_exp_f32_e32 v194, v194
	v_exp_f32_e32 v195, v195
	v_exp_f32_e32 v196, v196
	v_exp_f32_e32 v197, v197
	v_exp_f32_e32 v198, v198
	v_exp_f32_e32 v199, v199
	v_exp_f32_e32 v200, v200
	v_exp_f32_e32 v201, v201
	v_pk_add_f32 v[194:195], v[194:195], v[182:183]
	v_pk_add_f32 v[196:197], v[196:197], v[182:183]
	v_pk_add_f32 v[198:199], v[198:199], v[182:183]
	v_pk_add_f32 v[200:201], v[200:201], v[182:183]
	v_rcp_f32_e32 v194, v194
	v_rcp_f32_e32 v195, v195
	v_rcp_f32_e32 v196, v196
	v_rcp_f32_e32 v197, v197
	v_rcp_f32_e32 v198, v198
	v_rcp_f32_e32 v199, v199
	v_rcp_f32_e32 v200, v200
	v_rcp_f32_e32 v201, v201
	v_pk_mul_f32 v[186:187], v[76:77], v[194:195]
	v_pk_mul_f32 v[188:189], v[78:79], v[196:197]
	v_pk_mul_f32 v[190:191], v[72:73], v[198:199]
	v_pk_mul_f32 v[192:193], v[74:75], v[200:201]
	v_cvt_pk_f16_f32 v202, v186, v187
	v_cvt_pk_f16_f32 v203, v188, v189
	v_cvt_pk_f16_f32 v204, v190, v191
	v_cvt_pk_f16_f32 v205, v192, v193
	v_add_u32_e32 v185, s89, v184
	global_store_dwordx4 v185, v[202:205], s[8:9]
	v_pk_mul_f32 v[194:195], v[68:69], v[178:179]
	v_pk_mul_f32 v[196:197], v[70:71], v[178:179]
	v_pk_mul_f32 v[198:199], v[64:65], v[178:179]
	v_pk_mul_f32 v[200:201], v[66:67], v[178:179]
	v_exp_f32_e32 v194, v194
	v_exp_f32_e32 v195, v195
	v_exp_f32_e32 v196, v196
	v_exp_f32_e32 v197, v197
	v_exp_f32_e32 v198, v198
	v_exp_f32_e32 v199, v199
	v_exp_f32_e32 v200, v200
	v_exp_f32_e32 v201, v201
	v_pk_add_f32 v[194:195], v[194:195], v[182:183]
	v_pk_add_f32 v[196:197], v[196:197], v[182:183]
	v_pk_add_f32 v[198:199], v[198:199], v[182:183]
	v_pk_add_f32 v[200:201], v[200:201], v[182:183]
	v_rcp_f32_e32 v194, v194
	v_rcp_f32_e32 v195, v195
	v_rcp_f32_e32 v196, v196
	v_rcp_f32_e32 v197, v197
	v_rcp_f32_e32 v198, v198
	v_rcp_f32_e32 v199, v199
	v_rcp_f32_e32 v200, v200
	v_rcp_f32_e32 v201, v201
	v_pk_mul_f32 v[186:187], v[68:69], v[194:195]
	v_pk_mul_f32 v[188:189], v[70:71], v[196:197]
	v_pk_mul_f32 v[190:191], v[64:65], v[198:199]
	v_pk_mul_f32 v[192:193], v[66:67], v[200:201]
	v_cvt_pk_f16_f32 v206, v186, v187
	v_cvt_pk_f16_f32 v207, v188, v189
	v_cvt_pk_f16_f32 v208, v190, v191
	v_cvt_pk_f16_f32 v209, v192, v193
	s_add_u32 s53, s89, s95
	v_add_u32_e32 v185, s53, v184
	global_store_dwordx4 v185, v[206:209], s[8:9]
	s_mov_b32 s89, s94
	v_pk_mul_f32 v[194:195], v[60:61], v[178:179]
	v_pk_mul_f32 v[196:197], v[62:63], v[178:179]
	v_pk_mul_f32 v[198:199], v[56:57], v[178:179]
	v_pk_mul_f32 v[200:201], v[58:59], v[178:179]
	v_exp_f32_e32 v194, v194
	v_exp_f32_e32 v195, v195
	v_exp_f32_e32 v196, v196
	v_exp_f32_e32 v197, v197
	v_exp_f32_e32 v198, v198
	v_exp_f32_e32 v199, v199
	v_exp_f32_e32 v200, v200
	v_exp_f32_e32 v201, v201
	v_pk_add_f32 v[194:195], v[194:195], v[182:183]
	v_pk_add_f32 v[196:197], v[196:197], v[182:183]
	v_pk_add_f32 v[198:199], v[198:199], v[182:183]
	v_pk_add_f32 v[200:201], v[200:201], v[182:183]
	v_rcp_f32_e32 v194, v194
	v_rcp_f32_e32 v195, v195
	v_rcp_f32_e32 v196, v196
	v_rcp_f32_e32 v197, v197
	v_rcp_f32_e32 v198, v198
	v_rcp_f32_e32 v199, v199
	v_rcp_f32_e32 v200, v200
	v_rcp_f32_e32 v201, v201
	v_pk_mul_f32 v[186:187], v[60:61], v[194:195]
	v_pk_mul_f32 v[188:189], v[62:63], v[196:197]
	v_pk_mul_f32 v[190:191], v[56:57], v[198:199]
	v_pk_mul_f32 v[192:193], v[58:59], v[200:201]
	v_cvt_pk_f16_f32 v202, v186, v187
	v_cvt_pk_f16_f32 v203, v188, v189
	v_cvt_pk_f16_f32 v204, v190, v191
	v_cvt_pk_f16_f32 v205, v192, v193
	v_add_u32_e32 v185, s89, v184
	global_store_dwordx4 v185, v[202:205], s[8:9]
	v_pk_mul_f32 v[194:195], v[52:53], v[178:179]
	v_pk_mul_f32 v[196:197], v[54:55], v[178:179]
	v_pk_mul_f32 v[198:199], v[48:49], v[178:179]
	v_pk_mul_f32 v[200:201], v[50:51], v[178:179]
	v_exp_f32_e32 v194, v194
	v_exp_f32_e32 v195, v195
	v_exp_f32_e32 v196, v196
	v_exp_f32_e32 v197, v197
	v_exp_f32_e32 v198, v198
	v_exp_f32_e32 v199, v199
	v_exp_f32_e32 v200, v200
	v_exp_f32_e32 v201, v201
	v_pk_add_f32 v[194:195], v[194:195], v[182:183]
	v_pk_add_f32 v[196:197], v[196:197], v[182:183]
	v_pk_add_f32 v[198:199], v[198:199], v[182:183]
	v_pk_add_f32 v[200:201], v[200:201], v[182:183]
	v_rcp_f32_e32 v194, v194
	v_rcp_f32_e32 v195, v195
	v_rcp_f32_e32 v196, v196
	v_rcp_f32_e32 v197, v197
	v_rcp_f32_e32 v198, v198
	v_rcp_f32_e32 v199, v199
	v_rcp_f32_e32 v200, v200
	v_rcp_f32_e32 v201, v201
	v_pk_mul_f32 v[186:187], v[52:53], v[194:195]
	v_pk_mul_f32 v[188:189], v[54:55], v[196:197]
	v_pk_mul_f32 v[190:191], v[48:49], v[198:199]
	v_pk_mul_f32 v[192:193], v[50:51], v[200:201]
	v_cvt_pk_f16_f32 v206, v186, v187
	v_cvt_pk_f16_f32 v207, v188, v189
	v_cvt_pk_f16_f32 v208, v190, v191
	v_cvt_pk_f16_f32 v209, v192, v193
	s_add_u32 s53, s89, s95
	v_add_u32_e32 v185, s53, v184
	global_store_dwordx4 v185, v[206:209], s[8:9]
	s_add_u32 s89, s89, s39
	v_pk_mul_f32 v[194:195], v[44:45], v[178:179]
	v_pk_mul_f32 v[196:197], v[46:47], v[178:179]
	v_pk_mul_f32 v[198:199], v[40:41], v[178:179]
	v_pk_mul_f32 v[200:201], v[42:43], v[178:179]
	v_exp_f32_e32 v194, v194
	v_exp_f32_e32 v195, v195
	v_exp_f32_e32 v196, v196
	v_exp_f32_e32 v197, v197
	v_exp_f32_e32 v198, v198
	v_exp_f32_e32 v199, v199
	v_exp_f32_e32 v200, v200
	v_exp_f32_e32 v201, v201
	v_pk_add_f32 v[194:195], v[194:195], v[182:183]
	v_pk_add_f32 v[196:197], v[196:197], v[182:183]
	v_pk_add_f32 v[198:199], v[198:199], v[182:183]
	v_pk_add_f32 v[200:201], v[200:201], v[182:183]
	v_rcp_f32_e32 v194, v194
	v_rcp_f32_e32 v195, v195
	v_rcp_f32_e32 v196, v196
	v_rcp_f32_e32 v197, v197
	v_rcp_f32_e32 v198, v198
	v_rcp_f32_e32 v199, v199
	v_rcp_f32_e32 v200, v200
	v_rcp_f32_e32 v201, v201
	v_pk_mul_f32 v[186:187], v[44:45], v[194:195]
	v_pk_mul_f32 v[188:189], v[46:47], v[196:197]
	v_pk_mul_f32 v[190:191], v[40:41], v[198:199]
	v_pk_mul_f32 v[192:193], v[42:43], v[200:201]
	v_cvt_pk_f16_f32 v202, v186, v187
	v_cvt_pk_f16_f32 v203, v188, v189
	v_cvt_pk_f16_f32 v204, v190, v191
	v_cvt_pk_f16_f32 v205, v192, v193
	v_add_u32_e32 v185, s89, v184
	global_store_dwordx4 v185, v[202:205], s[8:9]
	v_pk_mul_f32 v[194:195], v[36:37], v[178:179]
	v_pk_mul_f32 v[196:197], v[38:39], v[178:179]
	v_pk_mul_f32 v[198:199], v[32:33], v[178:179]
	v_pk_mul_f32 v[200:201], v[34:35], v[178:179]
	v_exp_f32_e32 v194, v194
	v_exp_f32_e32 v195, v195
	v_exp_f32_e32 v196, v196
	v_exp_f32_e32 v197, v197
	v_exp_f32_e32 v198, v198
	v_exp_f32_e32 v199, v199
	v_exp_f32_e32 v200, v200
	v_exp_f32_e32 v201, v201
	v_pk_add_f32 v[194:195], v[194:195], v[182:183]
	v_pk_add_f32 v[196:197], v[196:197], v[182:183]
	v_pk_add_f32 v[198:199], v[198:199], v[182:183]
	v_pk_add_f32 v[200:201], v[200:201], v[182:183]
	v_rcp_f32_e32 v194, v194
	v_rcp_f32_e32 v195, v195
	v_rcp_f32_e32 v196, v196
	v_rcp_f32_e32 v197, v197
	v_rcp_f32_e32 v198, v198
	v_rcp_f32_e32 v199, v199
	v_rcp_f32_e32 v200, v200
	v_rcp_f32_e32 v201, v201
	v_pk_mul_f32 v[186:187], v[36:37], v[194:195]
	v_pk_mul_f32 v[188:189], v[38:39], v[196:197]
	v_pk_mul_f32 v[190:191], v[32:33], v[198:199]
	v_pk_mul_f32 v[192:193], v[34:35], v[200:201]
	v_cvt_pk_f16_f32 v206, v186, v187
	v_cvt_pk_f16_f32 v207, v188, v189
	v_cvt_pk_f16_f32 v208, v190, v191
	v_cvt_pk_f16_f32 v209, v192, v193
	s_add_u32 s53, s89, s95
	v_add_u32_e32 v185, s53, v184
	global_store_dwordx4 v185, v[206:209], s[8:9]
	s_add_u32 s89, s89, s39
	v_pk_mul_f32 v[194:195], v[28:29], v[178:179]
	v_pk_mul_f32 v[196:197], v[30:31], v[178:179]
	v_pk_mul_f32 v[198:199], v[24:25], v[178:179]
	v_pk_mul_f32 v[200:201], v[26:27], v[178:179]
	v_exp_f32_e32 v194, v194
	v_exp_f32_e32 v195, v195
	v_exp_f32_e32 v196, v196
	v_exp_f32_e32 v197, v197
	v_exp_f32_e32 v198, v198
	v_exp_f32_e32 v199, v199
	v_exp_f32_e32 v200, v200
	v_exp_f32_e32 v201, v201
	v_pk_add_f32 v[194:195], v[194:195], v[182:183]
	v_pk_add_f32 v[196:197], v[196:197], v[182:183]
	v_pk_add_f32 v[198:199], v[198:199], v[182:183]
	v_pk_add_f32 v[200:201], v[200:201], v[182:183]
	v_rcp_f32_e32 v194, v194
	v_rcp_f32_e32 v195, v195
	v_rcp_f32_e32 v196, v196
	v_rcp_f32_e32 v197, v197
	v_rcp_f32_e32 v198, v198
	v_rcp_f32_e32 v199, v199
	v_rcp_f32_e32 v200, v200
	v_rcp_f32_e32 v201, v201
	v_pk_mul_f32 v[186:187], v[28:29], v[194:195]
	v_pk_mul_f32 v[188:189], v[30:31], v[196:197]
	v_pk_mul_f32 v[190:191], v[24:25], v[198:199]
	v_pk_mul_f32 v[192:193], v[26:27], v[200:201]
	v_cvt_pk_f16_f32 v202, v186, v187
	v_cvt_pk_f16_f32 v203, v188, v189
	v_cvt_pk_f16_f32 v204, v190, v191
	v_cvt_pk_f16_f32 v205, v192, v193
	v_add_u32_e32 v185, s89, v184
	global_store_dwordx4 v185, v[202:205], s[8:9]
	v_pk_mul_f32 v[194:195], v[20:21], v[178:179]
	v_pk_mul_f32 v[196:197], v[22:23], v[178:179]
	v_pk_mul_f32 v[198:199], v[16:17], v[178:179]
	v_pk_mul_f32 v[200:201], v[18:19], v[178:179]
	v_exp_f32_e32 v194, v194
	v_exp_f32_e32 v195, v195
	v_exp_f32_e32 v196, v196
	v_exp_f32_e32 v197, v197
	v_exp_f32_e32 v198, v198
	v_exp_f32_e32 v199, v199
	v_exp_f32_e32 v200, v200
	v_exp_f32_e32 v201, v201
	v_pk_add_f32 v[194:195], v[194:195], v[182:183]
	v_pk_add_f32 v[196:197], v[196:197], v[182:183]
	v_pk_add_f32 v[198:199], v[198:199], v[182:183]
	v_pk_add_f32 v[200:201], v[200:201], v[182:183]
	v_rcp_f32_e32 v194, v194
	v_rcp_f32_e32 v195, v195
	v_rcp_f32_e32 v196, v196
	v_rcp_f32_e32 v197, v197
	v_rcp_f32_e32 v198, v198
	v_rcp_f32_e32 v199, v199
	v_rcp_f32_e32 v200, v200
	v_rcp_f32_e32 v201, v201
	v_pk_mul_f32 v[186:187], v[20:21], v[194:195]
	v_pk_mul_f32 v[188:189], v[22:23], v[196:197]
	v_pk_mul_f32 v[190:191], v[16:17], v[198:199]
	v_pk_mul_f32 v[192:193], v[18:19], v[200:201]
	v_cvt_pk_f16_f32 v206, v186, v187
	v_cvt_pk_f16_f32 v207, v188, v189
	v_cvt_pk_f16_f32 v208, v190, v191
	v_cvt_pk_f16_f32 v209, v192, v193
	s_add_u32 s53, s89, s95
	v_add_u32_e32 v185, s53, v184
	global_store_dwordx4 v185, v[206:209], s[8:9]
	s_add_u32 s89, s89, s39
	v_pk_mul_f32 v[194:195], v[12:13], v[178:179]
	v_pk_mul_f32 v[196:197], v[14:15], v[178:179]
	v_pk_mul_f32 v[198:199], v[8:9], v[178:179]
	v_pk_mul_f32 v[200:201], v[10:11], v[178:179]
	v_exp_f32_e32 v194, v194
	v_exp_f32_e32 v195, v195
	v_exp_f32_e32 v196, v196
	v_exp_f32_e32 v197, v197
	v_exp_f32_e32 v198, v198
	v_exp_f32_e32 v199, v199
	v_exp_f32_e32 v200, v200
	v_exp_f32_e32 v201, v201
	v_pk_add_f32 v[194:195], v[194:195], v[182:183]
	v_pk_add_f32 v[196:197], v[196:197], v[182:183]
	v_pk_add_f32 v[198:199], v[198:199], v[182:183]
	v_pk_add_f32 v[200:201], v[200:201], v[182:183]
	v_rcp_f32_e32 v194, v194
	v_rcp_f32_e32 v195, v195
	v_rcp_f32_e32 v196, v196
	v_rcp_f32_e32 v197, v197
	v_rcp_f32_e32 v198, v198
	v_rcp_f32_e32 v199, v199
	v_rcp_f32_e32 v200, v200
	v_rcp_f32_e32 v201, v201
	v_pk_mul_f32 v[186:187], v[12:13], v[194:195]
	v_pk_mul_f32 v[188:189], v[14:15], v[196:197]
	v_pk_mul_f32 v[190:191], v[8:9], v[198:199]
	v_pk_mul_f32 v[192:193], v[10:11], v[200:201]
	v_cvt_pk_f16_f32 v202, v186, v187
	v_cvt_pk_f16_f32 v203, v188, v189
	v_cvt_pk_f16_f32 v204, v190, v191
	v_cvt_pk_f16_f32 v205, v192, v193
	v_add_u32_e32 v185, s89, v184
	global_store_dwordx4 v185, v[202:205], s[8:9]
	v_pk_mul_f32 v[194:195], v[4:5], v[178:179]
	v_pk_mul_f32 v[196:197], v[6:7], v[178:179]
	v_pk_mul_f32 v[198:199], v[0:1], v[178:179]
	v_pk_mul_f32 v[200:201], v[2:3], v[178:179]
	v_exp_f32_e32 v194, v194
	v_exp_f32_e32 v195, v195
	v_exp_f32_e32 v196, v196
	v_exp_f32_e32 v197, v197
	v_exp_f32_e32 v198, v198
	v_exp_f32_e32 v199, v199
	v_exp_f32_e32 v200, v200
	v_exp_f32_e32 v201, v201
	v_pk_add_f32 v[194:195], v[194:195], v[182:183]
	v_pk_add_f32 v[196:197], v[196:197], v[182:183]
	v_pk_add_f32 v[198:199], v[198:199], v[182:183]
	v_pk_add_f32 v[200:201], v[200:201], v[182:183]
	v_rcp_f32_e32 v194, v194
	v_rcp_f32_e32 v195, v195
	v_rcp_f32_e32 v196, v196
	v_rcp_f32_e32 v197, v197
	v_rcp_f32_e32 v198, v198
	v_rcp_f32_e32 v199, v199
	v_rcp_f32_e32 v200, v200
	v_rcp_f32_e32 v201, v201
	v_pk_mul_f32 v[186:187], v[4:5], v[194:195]
	v_pk_mul_f32 v[188:189], v[6:7], v[196:197]
	v_pk_mul_f32 v[190:191], v[0:1], v[198:199]
	v_pk_mul_f32 v[192:193], v[2:3], v[200:201]
	v_cvt_pk_f16_f32 v206, v186, v187
	v_cvt_pk_f16_f32 v207, v188, v189
	v_cvt_pk_f16_f32 v208, v190, v191
	v_cvt_pk_f16_f32 v209, v192, v193
	s_add_u32 s53, s89, s95
	v_add_u32_e32 v185, s53, v184
	global_store_dwordx4 v185, v[206:209], s[8:9]
	s_branch .LBB0_993
